# hyena conv loops hand-scheduled: W fragment register ring (no rotation moves, x3 unroll), B fragments 4-quad ring loaded 4 groups ahead, no peeled tail; on top of K-split
# speedup vs baseline: 1.0686x; 1.0223x over previous
; DI f32x16 zero16() { f32x16 z; for (int i = 0; i < 16; ++i) z[i] = 0.f; return z; }
; DI void hy_conv(f32x16 (&acc)[4], const u16* abase, const u16* U, const u16* Zrow, int a0, int li, int g) {
; #pragma unroll
;   for (int i = 0; i < 4; ++i) acc[i] = zero16();
;   u32x4 W[14];
;   bf16x8 bf[8];
;   int d = a0 - 63;
; #pragma unroll
;   for (int x = 0; x < 14; ++x) W[x] = hy_afrag(abase, 8 * d + x - 7);
; DI void hyena_item(const P& p, int l, int c, char* smem) {
;     ...
;   {
;     const float w0 = cw[c], w1 = cw[1536 + c], w2 = cw[3072 + c], bs = cbias[c];
; #pragma unroll
;     for (int i = 0; i < 4; ++i) {
;       const int q = tid + NT * i;
;       const int bt = q >> 10, t8 = (q & 1023) * 8;
;       const u16* row = p.hyT + (size_t)c * HYP + bt * SEQ;
;       float o0[4], o1[4];
;       sconv4(row, t8, w0, w1, w2, bs, o0);
;       sconv4(row, t8 + 4, w0, w1, w2, bs, o1);
;       uint4 ov;
;       ov.x = pack2(o0[0], o0[1]); ov.y = pack2(o0[2], o0[3]); ov.z = pack2(o1[0], o1[1]); ov.w = pack2(o1[2], o1[3]);
;       *(uint4*)(U + (bt * 64 + (t8 >> 7)) * 136 + (t8 & 127)) = ov;
;     }
;   }
;   __syncthreads();
;   const float invn0 = 1.0f / (misc[4] + misc[5] + misc[6] + misc[7]);
;   const float invn1 = 1.0f / (misc[8] + misc[9] + misc[10] + misc[11]);
;   const u16* abase = (li & 1) ? (TbO + (8192 - li + 8 * g - 1)) : (TbE + (8192 - li + 8 * g));
;   const int bt = li >> 4;
;   const int a = a0 + (li & 15);
;   f32x16 acc[4];
;   if (cwv) hy_conv(acc, abase, U, Zrow, a0, li, g);
.LBB0_433:
	s_or_b64 exec, exec, s[78:79]
	s_waitcnt vmcnt(2)
	v_and_b32_e32 v26, 0xffff0000, v10
	v_mov_b32_e32 v18, v26
	v_lshlrev_b32_e32 v10, 16, v10
	v_pk_mul_f32 v[18:19], v[2:3], v[18:19]
	v_and_b32_e32 v12, 0xffff0000, v11
	s_waitcnt vmcnt(1)
	v_lshlrev_b32_e32 v13, 16, v14
	v_lshlrev_b32_e32 v27, 16, v11
	v_pk_fma_f32 v[2:3], v[2:3], v[10:11], v[18:19] op_sel:[0,0,1] op_sel_hi:[1,0,0]
	v_pk_mov_b32 v[28:29], v[26:27], v[12:13] op_sel:[1,0]
	v_pk_fma_f32 v[2:3], v[0:1], v[26:27], v[2:3]
	v_readlane_b32 s78, v248, 10
	v_pk_add_f32 v[10:11], v[4:5], v[2:3]
	v_pk_mul_f32 v[2:3], v[8:9], v[28:29]
	s_waitcnt vmcnt(0)
	v_and_b32_e32 v28, 0xffff0000, v16
	v_pk_fma_f32 v[2:3], v[6:7], v[26:27], v[2:3]
	v_lshlrev_b32_e32 v29, 16, v17
	v_pk_fma_f32 v[2:3], v[0:1], v[12:13], v[2:3]
	v_lshlrev_b32_e32 v13, 16, v16
	v_and_b32_e32 v27, 0xffff0000, v17
	v_mov_b32_e32 v26, v29
	v_mov_b32_e32 v16, v13
	v_mov_b32_e32 v17, v28
	v_pk_mul_f32 v[16:17], v[8:9], v[16:17]
	v_pk_mul_f32 v[8:9], v[8:9], v[26:27]
	v_pk_fma_f32 v[12:13], v[6:7], v[12:13], v[16:17]
	v_pk_fma_f32 v[6:7], v[6:7], v[28:29], v[8:9]
	v_mov_b32_e32 v14, v27
	v_pk_fma_f32 v[12:13], v[0:1], v[28:29], v[12:13]
	v_pk_fma_f32 v[0:1], v[0:1], v[14:15], v[6:7]
	v_pk_add_f32 v[18:19], v[4:5], v[2:3]
	v_pk_add_f32 v[0:1], v[4:5], v[0:1]
	v_pk_add_f32 v[12:13], v[4:5], v[12:13]
	v_cvt_pk_bf16_f32 v7, v0, v1
	v_lshrrev_b32_e32 v0, 7, v25
	v_lshl_or_b32 v0, v24, 6, v0
	v_and_b32_e32 v1, 0x78, v23
	v_mul_lo_u32 v0, v0, s97
	v_lshlrev_b32_e32 v1, 1, v1
	v_cvt_pk_bf16_f32 v4, v10, v11
	v_cvt_pk_bf16_f32 v5, v18, v19
	v_cvt_pk_bf16_f32 v6, v12, v13
	v_add3_u32 v0, s69, v0, v1
	ds_write_b128 v0, v[4:7]
	v_mov_b32_e32 v0, s78
	v_readlane_b32 s78, v248, 11
	v_lshrrev_b32_e32 v188, 5, v21
	v_and_b32_e32 v230, 31, v20
	v_mov_b32_e32 v1, s78
	s_waitcnt lgkmcnt(0)
	s_barrier
	ds_read_b128 v[68:71], v0
	ds_read_b128 v[64:67], v1
	v_and_b32_e32 v0, 1, v20
	v_lshlrev_b32_e32 v1, 3, v188
	v_readlane_b32 s78, v248, 12
	v_sub_u32_e32 v1, v1, v230
	v_cmp_eq_u32_e32 vcc, 0, v0
	v_mov_b32_e32 v3, s78
	v_lshlrev_b32_e32 v2, 4, v22
	v_cndmask_b32_e64 v0, v3, 0, vcc
	v_cndmask_b32_e32 v3, v217, v207, vcc
	v_lshlrev_b32_e32 v1, 1, v1
	v_and_b32_e32 v231, 48, v2
	v_add3_u32 v225, v0, v1, v3
	v_and_b32_e32 v223, 15, v20
	v_lshlrev_b32_e32 v0, 2, v230
	v_or_b32_e32 v226, 15, v231
	v_lshlrev_b32_e32 v222, 4, v188
	v_or_b32_e32 v227, 14, v231
	v_add_u32_e32 v229, v231, v223
	v_or_b32_e32 v228, 0xffffffc1, v2
	v_and_b32_e32 v224, 64, v0
	v_mov_b32_e32 v250, 40
	v_cndmask_b32_e64 v249, v250, 0, s[6:7]
	v_add_u32_e32 v228, v228, v249
	v_mov_b32_e32 v250, 39
	v_cndmask_b32_e64 v249, 0, v250, s[6:7]
	v_sub_u32_e32 v227, v227, v249
	v_mov_b32_e32 v249, 24
	v_mov_b32_e32 v250, -15
	v_cndmask_b32_e64 v250, v250, v249, s[6:7]
	s_and_b64 vcc, exec, s[6:7]
	s_cbranch_vccnz .Lhy_pf_skip
	s_or_b32 s78, s72, 0x200
	s_mul_hi_u32 s79, s78, 0x8080
	s_mul_i32 s78, s78, 0x8080
	s_add_u32 s78, s36, s78
	s_addc_u32 s79, s37, s79
	v_and_b32_e32 v240, 0xff, v198
	v_lshlrev_b32_e32 v240, 7, v240
	global_load_dword v251, v240, s[78:79]
	s_add_u32 s78, s78, 0x1010000
	s_addc_u32 s79, s79, 0
	global_load_dword v251, v240, s[78:79]
	s_add_u32 s78, s78, 0x1010000
	s_addc_u32 s79, s79, 0
	global_load_dword v251, v240, s[78:79]
.Lhy_pf_skip:
	s_mov_b64 s[78:79], exec
	v_mov_b32_e32 v234, v228
	v_add_u32_e32 v242, 0xffffff40, v225
	v_lshlrev_b32_e32 v241, 8, v234
	v_sub_u32_e32 v240, v242, v241
	ds_read2_b32 v[72:73], v240 offset0:104 offset1:105
	ds_read2_b32 v[74:75], v240 offset0:106 offset1:107
	ds_read2_b32 v[76:77], v240 offset0:96 offset1:97
	ds_read2_b32 v[78:79], v240 offset0:98 offset1:99
	ds_read2_b32 v[80:81], v240 offset0:88 offset1:89
	ds_read2_b32 v[82:83], v240 offset0:90 offset1:91
	ds_read2_b32 v[84:85], v240 offset0:80 offset1:81
	ds_read2_b32 v[86:87], v240 offset0:82 offset1:83
	ds_read2_b32 v[88:89], v240 offset0:72 offset1:73
	ds_read2_b32 v[90:91], v240 offset0:74 offset1:75
	ds_read2_b32 v[92:93], v240 offset0:64 offset1:65
	ds_read2_b32 v[94:95], v240 offset0:66 offset1:67
	ds_read2_b32 v[96:97], v240 offset0:56 offset1:57
	ds_read2_b32 v[98:99], v240 offset0:58 offset1:59
	ds_read2_b32 v[100:101], v240 offset0:48 offset1:49
	ds_read2_b32 v[102:103], v240 offset0:50 offset1:51
	ds_read2_b32 v[104:105], v240 offset0:40 offset1:41
	ds_read2_b32 v[106:107], v240 offset0:42 offset1:43
	ds_read2_b32 v[108:109], v240 offset0:32 offset1:33
	ds_read2_b32 v[110:111], v240 offset0:34 offset1:35
	ds_read2_b32 v[112:113], v240 offset0:24 offset1:25
	ds_read2_b32 v[114:115], v240 offset0:26 offset1:27
	ds_read2_b32 v[116:117], v240 offset0:16 offset1:17
	ds_read2_b32 v[118:119], v240 offset0:18 offset1:19
	ds_read2_b32 v[120:121], v240 offset0:8 offset1:9
	ds_read2_b32 v[122:123], v240 offset0:10 offset1:11
	ds_read2_b32 v[124:125], v240 offset0:0 offset1:1
	ds_read2_b32 v[126:127], v240 offset0:2 offset1:3
	v_add_u32_e32 v241, v229, v224
	v_sub_u32_e32 v241, v241, v234
	v_mov_b32_e32 v244, s69
	v_mad_u32_u24 v236, v241, s97, v244
	v_add_u32_e32 v236, v236, v222
	v_sub_u32_e32 v235, v229, v234
	s_mov_b32 s99, 0x18880
	v_add_u32_e32 v243, s99, v222
	v_cmp_gt_u32_e32 vcc, 64, v235
	s_movk_i32 s98, 13
	v_mov_b32_e32 v0, 0
	v_cndmask_b32_e32 v237, v243, v236, vcc
	ds_read_b128 v[168:171], v237 offset:0
	ds_read_b128 v[172:175], v237 offset:32
	ds_read_b128 v[176:179], v237 offset:64
	ds_read_b128 v[180:183], v237 offset:96
	v_mov_b32_e32 v1, v0
	v_mov_b32_e32 v2, v0
	v_mov_b32_e32 v3, v0
	v_mov_b32_e32 v4, v0
	v_mov_b32_e32 v5, v0
	v_mov_b32_e32 v6, v0
	v_mov_b32_e32 v7, v0
	v_mov_b32_e32 v8, v0
	v_mov_b32_e32 v9, v0
	v_mov_b32_e32 v10, v0
	v_mov_b32_e32 v11, v0
	v_mov_b32_e32 v12, v0
	v_mov_b32_e32 v13, v0
	v_mov_b32_e32 v14, v0
	v_mov_b32_e32 v15, v0
	v_mov_b32_e32 v16, v0
	v_mov_b32_e32 v17, v0
	v_mov_b32_e32 v18, v0
	v_mov_b32_e32 v19, v0
	v_mov_b32_e32 v20, v0
	v_mov_b32_e32 v21, v0
	v_mov_b32_e32 v22, v0
	v_mov_b32_e32 v23, v0
	v_mov_b32_e32 v24, v0
	v_mov_b32_e32 v25, v0
	v_mov_b32_e32 v26, v0
	v_mov_b32_e32 v27, v0
	v_mov_b32_e32 v28, v0
	v_mov_b32_e32 v29, v0
	v_mov_b32_e32 v30, v0
	v_mov_b32_e32 v31, v0
	v_mov_b32_e32 v32, v0
	v_mov_b32_e32 v33, v0
	v_mov_b32_e32 v34, v0
	v_mov_b32_e32 v35, v0
	v_mov_b32_e32 v36, v0
	v_mov_b32_e32 v37, v0
	v_mov_b32_e32 v38, v0
	v_mov_b32_e32 v39, v0
	v_mov_b32_e32 v40, v0
	v_mov_b32_e32 v41, v0
	v_mov_b32_e32 v42, v0
	v_mov_b32_e32 v43, v0
	v_mov_b32_e32 v44, v0
	v_mov_b32_e32 v45, v0
	v_mov_b32_e32 v46, v0
	v_mov_b32_e32 v47, v0
	v_mov_b32_e32 v48, v0
	v_mov_b32_e32 v49, v0
	v_mov_b32_e32 v50, v0
	v_mov_b32_e32 v51, v0
	v_mov_b32_e32 v52, v0
	v_mov_b32_e32 v53, v0
	v_mov_b32_e32 v54, v0
	v_mov_b32_e32 v55, v0
	v_mov_b32_e32 v56, v0
	v_mov_b32_e32 v57, v0
	v_mov_b32_e32 v58, v0
	v_mov_b32_e32 v59, v0
	v_mov_b32_e32 v60, v0
	v_mov_b32_e32 v61, v0
	v_mov_b32_e32 v62, v0
	v_mov_b32_e32 v63, v0
	s_waitcnt lgkmcnt(0)
; #define MFMA(a, b, c) __builtin_amdgcn_mfma_f32_32x32x16_bf16((a), (b), (c), 0, 0, 0)
; DI void hy_conv(f32x16 (&acc)[4], const u16* abase, const u16* U, const u16* Zrow, int a0, int li, int g) {
;     ...
;   for (; d <= a0 + 15; ++d) {
;     hy_bfrag(bf, U, Zrow, a0, li, g, d);
;     u32x4 Wn[8];
;     const int dn = (d < a0 + 15) ? d + 1 : d;
; #pragma unroll
;     for (int x = 0; x < 8; ++x) Wn[x] = hy_afrag(abase, 8 * dn + x - 1);
; #pragma unroll
;     for (int kc = 0; kc < 8; ++kc)
; #pragma unroll
;       for (int I = 0; I < 4; ++I) acc[I] = MFMA(__builtin_bit_cast(bf16x8, W[2 * I - kc + 7]), bf[kc], acc[I]);
; #pragma unroll
;     for (int x = 0; x < 6; ++x) W[x] = W[x + 8];
; #pragma unroll
;     for (int x = 0; x < 8; ++x) W[x + 6] = Wn[x];
.Lhc0_loop:
	v_add_u32_e32 v234, 1, v234
	v_min_i32_e32 v241, v234, v226
	v_lshlrev_b32_e32 v241, 8, v241
	v_sub_u32_e32 v240, v242, v241
	s_waitcnt lgkmcnt(9)
	v_mfma_f32_32x32x16_bf16 v[48:63], v[100:103], v[168:171], v[48:63]
	v_add_u32_e32 v235, -1, v235
	v_mfma_f32_32x32x16_bf16 v[32:47], v[108:111], v[168:171], v[32:47]
	v_add_u32_e32 v236, 0xfffffef0, v236
	ds_read2_b32 v[132:133], v240 offset0:48 offset1:49
	v_mfma_f32_32x32x16_bf16 v[16:31], v[116:119], v[168:171], v[16:31]
	v_cmp_gt_u32_e32 vcc, 64, v235
	ds_read2_b32 v[134:135], v240 offset0:50 offset1:51
	v_mfma_f32_32x32x16_bf16 v[0:15], v[124:127], v[168:171], v[0:15]
	ds_read_b128 v[168:171], v237 offset:128
	s_waitcnt lgkmcnt(9)
	v_mfma_f32_32x32x16_bf16 v[48:63], v[96:99], v[172:175], v[48:63]
	v_mfma_f32_32x32x16_bf16 v[32:47], v[104:107], v[172:175], v[32:47]
	v_cndmask_b32_e32 v238, v243, v236, vcc
	ds_read2_b32 v[140:141], v240 offset0:32 offset1:33
	s_waitcnt lgkmcnt(8)
	v_mfma_f32_32x32x16_bf16 v[16:31], v[112:115], v[172:175], v[16:31]
	ds_read2_b32 v[142:143], v240 offset0:34 offset1:35
	s_waitcnt lgkmcnt(6)
	v_mfma_f32_32x32x16_bf16 v[0:15], v[120:123], v[172:175], v[0:15]
	ds_read_b128 v[172:175], v237 offset:160
	v_mfma_f32_32x32x16_bf16 v[48:63], v[92:95], v[176:179], v[48:63]
	v_mfma_f32_32x32x16_bf16 v[32:47], v[100:103], v[176:179], v[32:47]
	ds_read2_b32 v[148:149], v240 offset0:16 offset1:17
	v_mfma_f32_32x32x16_bf16 v[16:31], v[108:111], v[176:179], v[16:31]
	ds_read2_b32 v[150:151], v240 offset0:18 offset1:19
	v_mfma_f32_32x32x16_bf16 v[0:15], v[116:119], v[176:179], v[0:15]
	ds_read_b128 v[176:179], v237 offset:192
	s_waitcnt lgkmcnt(9)
	v_mfma_f32_32x32x16_bf16 v[48:63], v[88:91], v[180:183], v[48:63]
	v_mfma_f32_32x32x16_bf16 v[32:47], v[96:99], v[180:183], v[32:47]
	ds_read2_b32 v[156:157], v240 offset0:0 offset1:1
	v_mfma_f32_32x32x16_bf16 v[16:31], v[104:107], v[180:183], v[16:31]
	ds_read2_b32 v[158:159], v240 offset0:2 offset1:3
	v_mfma_f32_32x32x16_bf16 v[0:15], v[112:115], v[180:183], v[0:15]
	ds_read_b128 v[180:183], v237 offset:224
	s_waitcnt lgkmcnt(9)
	v_mfma_f32_32x32x16_bf16 v[48:63], v[84:87], v[168:171], v[48:63]
	v_mfma_f32_32x32x16_bf16 v[32:47], v[92:95], v[168:171], v[32:47]
	ds_read2_b32 v[128:129], v240 offset0:56 offset1:57
	v_mfma_f32_32x32x16_bf16 v[16:31], v[100:103], v[168:171], v[16:31]
	ds_read2_b32 v[130:131], v240 offset0:58 offset1:59
	v_mfma_f32_32x32x16_bf16 v[0:15], v[108:111], v[168:171], v[0:15]
	ds_read_b128 v[168:171], v238 offset:0
	s_waitcnt lgkmcnt(9)
	v_mfma_f32_32x32x16_bf16 v[48:63], v[80:83], v[172:175], v[48:63]
	v_mfma_f32_32x32x16_bf16 v[32:47], v[88:91], v[172:175], v[32:47]
	ds_read2_b32 v[136:137], v240 offset0:40 offset1:41
	v_mfma_f32_32x32x16_bf16 v[16:31], v[96:99], v[172:175], v[16:31]
	ds_read2_b32 v[138:139], v240 offset0:42 offset1:43
	v_mfma_f32_32x32x16_bf16 v[0:15], v[104:107], v[172:175], v[0:15]
	ds_read_b128 v[172:175], v238 offset:32
	s_waitcnt lgkmcnt(9)
	v_mfma_f32_32x32x16_bf16 v[48:63], v[76:79], v[176:179], v[48:63]
	v_mfma_f32_32x32x16_bf16 v[32:47], v[84:87], v[176:179], v[32:47]
	ds_read2_b32 v[144:145], v240 offset0:24 offset1:25
	v_mfma_f32_32x32x16_bf16 v[16:31], v[92:95], v[176:179], v[16:31]
	ds_read2_b32 v[146:147], v240 offset0:26 offset1:27
	v_mfma_f32_32x32x16_bf16 v[0:15], v[100:103], v[176:179], v[0:15]
	ds_read_b128 v[176:179], v238 offset:64
	s_waitcnt lgkmcnt(9)
	v_mfma_f32_32x32x16_bf16 v[48:63], v[72:75], v[180:183], v[48:63]
	v_mfma_f32_32x32x16_bf16 v[32:47], v[80:83], v[180:183], v[32:47]
	ds_read2_b32 v[152:153], v240 offset0:8 offset1:9
	v_mfma_f32_32x32x16_bf16 v[16:31], v[88:91], v[180:183], v[16:31]
	ds_read2_b32 v[154:155], v240 offset0:10 offset1:11
	v_mfma_f32_32x32x16_bf16 v[0:15], v[96:99], v[180:183], v[0:15]
	ds_read_b128 v[180:183], v238 offset:96
	v_add_u32_e32 v234, 1, v234
	v_min_i32_e32 v241, v234, v226
	v_lshlrev_b32_e32 v241, 8, v241
	v_sub_u32_e32 v240, v242, v241
	s_waitcnt lgkmcnt(9)
	v_mfma_f32_32x32x16_bf16 v[48:63], v[132:135], v[168:171], v[48:63]
	v_add_u32_e32 v235, -1, v235
	v_mfma_f32_32x32x16_bf16 v[32:47], v[140:143], v[168:171], v[32:47]
	v_add_u32_e32 v236, 0xfffffef0, v236
	ds_read2_b32 v[164:165], v240 offset0:48 offset1:49
	v_mfma_f32_32x32x16_bf16 v[16:31], v[148:151], v[168:171], v[16:31]
	v_cmp_gt_u32_e32 vcc, 64, v235
	ds_read2_b32 v[166:167], v240 offset0:50 offset1:51
	v_mfma_f32_32x32x16_bf16 v[0:15], v[156:159], v[168:171], v[0:15]
	ds_read_b128 v[168:171], v238 offset:128
	s_waitcnt lgkmcnt(9)
	v_mfma_f32_32x32x16_bf16 v[48:63], v[128:131], v[172:175], v[48:63]
	v_mfma_f32_32x32x16_bf16 v[32:47], v[136:139], v[172:175], v[32:47]
	v_cndmask_b32_e32 v239, v243, v236, vcc
	ds_read2_b32 v[76:77], v240 offset0:32 offset1:33
	s_waitcnt lgkmcnt(8)
	v_mfma_f32_32x32x16_bf16 v[16:31], v[144:147], v[172:175], v[16:31]
	ds_read2_b32 v[78:79], v240 offset0:34 offset1:35
	s_waitcnt lgkmcnt(6)
	v_mfma_f32_32x32x16_bf16 v[0:15], v[152:155], v[172:175], v[0:15]
	ds_read_b128 v[172:175], v238 offset:160
	v_mfma_f32_32x32x16_bf16 v[48:63], v[124:127], v[176:179], v[48:63]
	v_mfma_f32_32x32x16_bf16 v[32:47], v[132:135], v[176:179], v[32:47]
	ds_read2_b32 v[84:85], v240 offset0:16 offset1:17
	v_mfma_f32_32x32x16_bf16 v[16:31], v[140:143], v[176:179], v[16:31]
	ds_read2_b32 v[86:87], v240 offset0:18 offset1:19
	v_mfma_f32_32x32x16_bf16 v[0:15], v[148:151], v[176:179], v[0:15]
	ds_read_b128 v[176:179], v238 offset:192
	s_waitcnt lgkmcnt(9)
; #define MFMA(a, b, c) __builtin_amdgcn_mfma_f32_32x32x16_bf16((a), (b), (c), 0, 0, 0)
; DI void hy_conv(f32x16 (&acc)[4], const u16* abase, const u16* U, const u16* Zrow, int a0, int li, int g) {
;     ...
;   for (; d <= a0 + 15; ++d) {
;     hy_bfrag(bf, U, Zrow, a0, li, g, d);
;     u32x4 Wn[8];
;     const int dn = (d < a0 + 15) ? d + 1 : d;
; #pragma unroll
;     for (int x = 0; x < 8; ++x) Wn[x] = hy_afrag(abase, 8 * dn + x - 1);
; #pragma unroll
;     for (int kc = 0; kc < 8; ++kc)
; #pragma unroll
;       for (int I = 0; I < 4; ++I) acc[I] = MFMA(__builtin_bit_cast(bf16x8, W[2 * I - kc + 7]), bf[kc], acc[I]);
; #pragma unroll
;     for (int x = 0; x < 6; ++x) W[x] = W[x + 8];
; #pragma unroll
;     for (int x = 0; x < 8; ++x) W[x + 6] = Wn[x];
	v_mfma_f32_32x32x16_bf16 v[48:63], v[120:123], v[180:183], v[48:63]
	v_mfma_f32_32x32x16_bf16 v[32:47], v[128:131], v[180:183], v[32:47]
	ds_read2_b32 v[92:93], v240 offset0:0 offset1:1
	v_mfma_f32_32x32x16_bf16 v[16:31], v[136:139], v[180:183], v[16:31]
	ds_read2_b32 v[94:95], v240 offset0:2 offset1:3
	v_mfma_f32_32x32x16_bf16 v[0:15], v[144:147], v[180:183], v[0:15]
	ds_read_b128 v[180:183], v238 offset:224
	s_waitcnt lgkmcnt(9)
	v_mfma_f32_32x32x16_bf16 v[48:63], v[116:119], v[168:171], v[48:63]
	v_mfma_f32_32x32x16_bf16 v[32:47], v[124:127], v[168:171], v[32:47]
	ds_read2_b32 v[160:161], v240 offset0:56 offset1:57
	v_mfma_f32_32x32x16_bf16 v[16:31], v[132:135], v[168:171], v[16:31]
	ds_read2_b32 v[162:163], v240 offset0:58 offset1:59
	v_mfma_f32_32x32x16_bf16 v[0:15], v[140:143], v[168:171], v[0:15]
	ds_read_b128 v[168:171], v239 offset:0
	s_waitcnt lgkmcnt(9)
	v_mfma_f32_32x32x16_bf16 v[48:63], v[112:115], v[172:175], v[48:63]
	v_mfma_f32_32x32x16_bf16 v[32:47], v[120:123], v[172:175], v[32:47]
	ds_read2_b32 v[72:73], v240 offset0:40 offset1:41
	v_mfma_f32_32x32x16_bf16 v[16:31], v[128:131], v[172:175], v[16:31]
	ds_read2_b32 v[74:75], v240 offset0:42 offset1:43
	v_mfma_f32_32x32x16_bf16 v[0:15], v[136:139], v[172:175], v[0:15]
	ds_read_b128 v[172:175], v239 offset:32
	s_waitcnt lgkmcnt(9)
	v_mfma_f32_32x32x16_bf16 v[48:63], v[108:111], v[176:179], v[48:63]
	v_mfma_f32_32x32x16_bf16 v[32:47], v[116:119], v[176:179], v[32:47]
	ds_read2_b32 v[80:81], v240 offset0:24 offset1:25
	v_mfma_f32_32x32x16_bf16 v[16:31], v[124:127], v[176:179], v[16:31]
	ds_read2_b32 v[82:83], v240 offset0:26 offset1:27
	v_mfma_f32_32x32x16_bf16 v[0:15], v[132:135], v[176:179], v[0:15]
	ds_read_b128 v[176:179], v239 offset:64
	s_waitcnt lgkmcnt(9)
	v_mfma_f32_32x32x16_bf16 v[48:63], v[104:107], v[180:183], v[48:63]
	v_mfma_f32_32x32x16_bf16 v[32:47], v[112:115], v[180:183], v[32:47]
	ds_read2_b32 v[88:89], v240 offset0:8 offset1:9
	v_mfma_f32_32x32x16_bf16 v[16:31], v[120:123], v[180:183], v[16:31]
	ds_read2_b32 v[90:91], v240 offset0:10 offset1:11
	v_mfma_f32_32x32x16_bf16 v[0:15], v[128:131], v[180:183], v[0:15]
	ds_read_b128 v[180:183], v239 offset:96
	v_add_u32_e32 v234, 1, v234
	v_min_i32_e32 v241, v234, v226
	v_lshlrev_b32_e32 v241, 8, v241
	v_sub_u32_e32 v240, v242, v241
	s_waitcnt lgkmcnt(9)
	v_mfma_f32_32x32x16_bf16 v[48:63], v[164:167], v[168:171], v[48:63]
	v_add_u32_e32 v235, -1, v235
	v_mfma_f32_32x32x16_bf16 v[32:47], v[76:79], v[168:171], v[32:47]
	v_add_u32_e32 v236, 0xfffffef0, v236
	ds_read2_b32 v[100:101], v240 offset0:48 offset1:49
	v_mfma_f32_32x32x16_bf16 v[16:31], v[84:87], v[168:171], v[16:31]
	v_cmp_gt_u32_e32 vcc, 64, v235
	ds_read2_b32 v[102:103], v240 offset0:50 offset1:51
	v_mfma_f32_32x32x16_bf16 v[0:15], v[92:95], v[168:171], v[0:15]
	ds_read_b128 v[168:171], v239 offset:128
	s_waitcnt lgkmcnt(9)
	v_mfma_f32_32x32x16_bf16 v[48:63], v[160:163], v[172:175], v[48:63]
	v_mfma_f32_32x32x16_bf16 v[32:47], v[72:75], v[172:175], v[32:47]
	v_cndmask_b32_e32 v237, v243, v236, vcc
	ds_read2_b32 v[108:109], v240 offset0:32 offset1:33
	s_waitcnt lgkmcnt(8)
	v_mfma_f32_32x32x16_bf16 v[16:31], v[80:83], v[172:175], v[16:31]
	ds_read2_b32 v[110:111], v240 offset0:34 offset1:35
	s_waitcnt lgkmcnt(6)
	v_mfma_f32_32x32x16_bf16 v[0:15], v[88:91], v[172:175], v[0:15]
	ds_read_b128 v[172:175], v239 offset:160
	v_mfma_f32_32x32x16_bf16 v[48:63], v[156:159], v[176:179], v[48:63]
	v_mfma_f32_32x32x16_bf16 v[32:47], v[164:167], v[176:179], v[32:47]
	ds_read2_b32 v[116:117], v240 offset0:16 offset1:17
	v_mfma_f32_32x32x16_bf16 v[16:31], v[76:79], v[176:179], v[16:31]
	ds_read2_b32 v[118:119], v240 offset0:18 offset1:19
	v_mfma_f32_32x32x16_bf16 v[0:15], v[84:87], v[176:179], v[0:15]
	ds_read_b128 v[176:179], v239 offset:192
	s_waitcnt lgkmcnt(9)
	v_mfma_f32_32x32x16_bf16 v[48:63], v[152:155], v[180:183], v[48:63]
	v_mfma_f32_32x32x16_bf16 v[32:47], v[160:163], v[180:183], v[32:47]
	ds_read2_b32 v[124:125], v240 offset0:0 offset1:1
	v_mfma_f32_32x32x16_bf16 v[16:31], v[72:75], v[180:183], v[16:31]
	ds_read2_b32 v[126:127], v240 offset0:2 offset1:3
	v_mfma_f32_32x32x16_bf16 v[0:15], v[80:83], v[180:183], v[0:15]
	ds_read_b128 v[180:183], v239 offset:224
	s_waitcnt lgkmcnt(9)
	v_mfma_f32_32x32x16_bf16 v[48:63], v[148:151], v[168:171], v[48:63]
	v_mfma_f32_32x32x16_bf16 v[32:47], v[156:159], v[168:171], v[32:47]
	ds_read2_b32 v[96:97], v240 offset0:56 offset1:57
	v_mfma_f32_32x32x16_bf16 v[16:31], v[164:167], v[168:171], v[16:31]
	ds_read2_b32 v[98:99], v240 offset0:58 offset1:59
	v_mfma_f32_32x32x16_bf16 v[0:15], v[76:79], v[168:171], v[0:15]
	ds_read_b128 v[168:171], v237 offset:0
	s_waitcnt lgkmcnt(9)
	v_mfma_f32_32x32x16_bf16 v[48:63], v[144:147], v[172:175], v[48:63]
	v_mfma_f32_32x32x16_bf16 v[32:47], v[152:155], v[172:175], v[32:47]
	ds_read2_b32 v[104:105], v240 offset0:40 offset1:41
	v_mfma_f32_32x32x16_bf16 v[16:31], v[160:163], v[172:175], v[16:31]
	ds_read2_b32 v[106:107], v240 offset0:42 offset1:43
	v_mfma_f32_32x32x16_bf16 v[0:15], v[72:75], v[172:175], v[0:15]
	ds_read_b128 v[172:175], v237 offset:32
	s_waitcnt lgkmcnt(9)
	v_mfma_f32_32x32x16_bf16 v[48:63], v[140:143], v[176:179], v[48:63]
	v_mfma_f32_32x32x16_bf16 v[32:47], v[148:151], v[176:179], v[32:47]
	ds_read2_b32 v[112:113], v240 offset0:24 offset1:25
	v_mfma_f32_32x32x16_bf16 v[16:31], v[156:159], v[176:179], v[16:31]
	ds_read2_b32 v[114:115], v240 offset0:26 offset1:27
	v_mfma_f32_32x32x16_bf16 v[0:15], v[164:167], v[176:179], v[0:15]
	ds_read_b128 v[176:179], v237 offset:64
	s_waitcnt lgkmcnt(9)
	v_mfma_f32_32x32x16_bf16 v[48:63], v[136:139], v[180:183], v[48:63]
	v_mfma_f32_32x32x16_bf16 v[32:47], v[144:147], v[180:183], v[32:47]
	ds_read2_b32 v[120:121], v240 offset0:8 offset1:9
	v_mfma_f32_32x32x16_bf16 v[16:31], v[152:155], v[180:183], v[16:31]
	ds_read2_b32 v[122:123], v240 offset0:10 offset1:11
	v_mfma_f32_32x32x16_bf16 v[0:15], v[160:163], v[180:183], v[0:15]
	ds_read_b128 v[180:183], v237 offset:96
	s_add_i32 s98, s98, -1
	s_cmp_lg_u32 s98, 0
	s_cbranch_scc1 .Lhc0_loop
; #define MFMA(a, b, c) __builtin_amdgcn_mfma_f32_32x32x16_bf16((a), (b), (c), 0, 0, 0)
; DI void hy_conv(f32x16 (&acc)[4], const u16* abase, const u16* U, const u16* Zrow, int a0, int li, int g) {
;     ...
;   for (; d <= a0 + 15; ++d) {
;     hy_bfrag(bf, U, Zrow, a0, li, g, d);
;     u32x4 Wn[8];
;     const int dn = (d < a0 + 15) ? d + 1 : d;
; #pragma unroll
;     for (int x = 0; x < 8; ++x) Wn[x] = hy_afrag(abase, 8 * dn + x - 1);
; #pragma unroll
;     for (int kc = 0; kc < 8; ++kc)
; #pragma unroll
;       for (int I = 0; I < 4; ++I) acc[I] = MFMA(__builtin_bit_cast(bf16x8, W[2 * I - kc + 7]), bf[kc], acc[I]);
; #pragma unroll
;     for (int x = 0; x < 6; ++x) W[x] = W[x + 8];
; #pragma unroll
;     for (int x = 0; x < 8; ++x) W[x + 6] = Wn[x];
; DI void hyena_item(const P& p, int l, int c, char* smem) {
;     ...
;   if (cwv) hy_conv(acc, abase, U, Zrow, a0, li, g);
;   __syncthreads();
	v_cmp_lt_i32_e32 vcc, 0, v250
	s_cbranch_vccz .Lhc0_done
	s_waitcnt lgkmcnt(9)
	v_mfma_f32_32x32x16_bf16 v[48:63], v[100:103], v[168:171], v[48:63]
	v_mfma_f32_32x32x16_bf16 v[32:47], v[108:111], v[168:171], v[32:47]
	v_mfma_f32_32x32x16_bf16 v[16:31], v[116:119], v[168:171], v[16:31]
	v_mfma_f32_32x32x16_bf16 v[0:15], v[124:127], v[168:171], v[0:15]
	ds_read_b128 v[168:171], v237 offset:128
	s_waitcnt lgkmcnt(7)
	v_mfma_f32_32x32x16_bf16 v[48:63], v[96:99], v[172:175], v[48:63]
	v_mfma_f32_32x32x16_bf16 v[32:47], v[104:107], v[172:175], v[32:47]
	s_waitcnt lgkmcnt(5)
	v_mfma_f32_32x32x16_bf16 v[16:31], v[112:115], v[172:175], v[16:31]
	s_waitcnt lgkmcnt(2)
	v_mfma_f32_32x32x16_bf16 v[0:15], v[120:123], v[172:175], v[0:15]
	ds_read_b128 v[172:175], v237 offset:160
	v_mfma_f32_32x32x16_bf16 v[48:63], v[92:95], v[176:179], v[48:63]
	v_mfma_f32_32x32x16_bf16 v[32:47], v[100:103], v[176:179], v[32:47]
	v_mfma_f32_32x32x16_bf16 v[16:31], v[108:111], v[176:179], v[16:31]
	v_mfma_f32_32x32x16_bf16 v[0:15], v[116:119], v[176:179], v[0:15]
	ds_read_b128 v[176:179], v237 offset:192
	s_waitcnt lgkmcnt(3)
	v_mfma_f32_32x32x16_bf16 v[48:63], v[88:91], v[180:183], v[48:63]
	v_mfma_f32_32x32x16_bf16 v[32:47], v[96:99], v[180:183], v[32:47]
	v_mfma_f32_32x32x16_bf16 v[16:31], v[104:107], v[180:183], v[16:31]
	v_mfma_f32_32x32x16_bf16 v[0:15], v[112:115], v[180:183], v[0:15]
	ds_read_b128 v[180:183], v237 offset:224
	s_waitcnt lgkmcnt(3)
	v_mfma_f32_32x32x16_bf16 v[48:63], v[84:87], v[168:171], v[48:63]
	v_mfma_f32_32x32x16_bf16 v[32:47], v[92:95], v[168:171], v[32:47]
	v_mfma_f32_32x32x16_bf16 v[16:31], v[100:103], v[168:171], v[16:31]
	v_mfma_f32_32x32x16_bf16 v[0:15], v[108:111], v[168:171], v[0:15]
	s_waitcnt lgkmcnt(2)
	v_mfma_f32_32x32x16_bf16 v[48:63], v[80:83], v[172:175], v[48:63]
	v_mfma_f32_32x32x16_bf16 v[32:47], v[88:91], v[172:175], v[32:47]
	v_mfma_f32_32x32x16_bf16 v[16:31], v[96:99], v[172:175], v[16:31]
	v_mfma_f32_32x32x16_bf16 v[0:15], v[104:107], v[172:175], v[0:15]
	s_waitcnt lgkmcnt(1)
	v_mfma_f32_32x32x16_bf16 v[48:63], v[76:79], v[176:179], v[48:63]
	v_mfma_f32_32x32x16_bf16 v[32:47], v[84:87], v[176:179], v[32:47]
	v_mfma_f32_32x32x16_bf16 v[16:31], v[92:95], v[176:179], v[16:31]
	v_mfma_f32_32x32x16_bf16 v[0:15], v[100:103], v[176:179], v[0:15]
	s_waitcnt lgkmcnt(0)
	v_mfma_f32_32x32x16_bf16 v[48:63], v[72:75], v[180:183], v[48:63]
	v_mfma_f32_32x32x16_bf16 v[32:47], v[80:83], v[180:183], v[32:47]
	v_mfma_f32_32x32x16_bf16 v[16:31], v[88:91], v[180:183], v[16:31]
	v_mfma_f32_32x32x16_bf16 v[0:15], v[96:99], v[180:183], v[0:15]
.Lhc0_done:
.LBB0_437:
	s_or_b64 exec, exec, s[78:79]
	v_or_b32_e32 v231, v231, v223
	v_lshrrev_b32_e32 v230, 4, v230
	v_lshlrev_b32_e32 v186, 2, v188
	v_lshlrev_b32_e32 v187, 7, v231
	v_lshlrev_b32_e32 v232, 13, v230
	v_lshlrev_b32_e32 v184, 14, v230
	v_or_b32_e32 v233, v187, v186
	s_waitcnt lgkmcnt(0)
	s_barrier
	v_and_b32_e32 v249, 0xff, v198
	v_lshlrev_b32_e32 v249, 4, v249
	v_cmp_lt_i32_e32 vcc, 0, v250
	s_cbranch_vccnz .Lhy0_rd_main
	s_nop 15
	ds_write_b128 v249, v[0:3] offset:0
	ds_write_b128 v249, v[4:7] offset:4096
	ds_write_b128 v249, v[8:11] offset:8192
	ds_write_b128 v249, v[12:15] offset:12288
	ds_write_b128 v249, v[16:19] offset:16384
	ds_write_b128 v249, v[20:23] offset:20480
	ds_write_b128 v249, v[24:27] offset:24576
	ds_write_b128 v249, v[28:31] offset:28672
	ds_write_b128 v249, v[32:35] offset:32768
	ds_write_b128 v249, v[36:39] offset:36864
	ds_write_b128 v249, v[40:43] offset:40960
	ds_write_b128 v249, v[44:47] offset:45056
	ds_write_b128 v249, v[48:51] offset:49152
	ds_write_b128 v249, v[52:55] offset:53248
	ds_write_b128 v249, v[56:59] offset:57344
	ds_write_b128 v249, v[60:63] offset:61440
	s_waitcnt lgkmcnt(0)
.Lhy0_rd_main:
	s_barrier
	v_cmp_lt_i32_e32 vcc, 0, v250
	s_cbranch_vccz .Lhy0_rd_done
	ds_read_b128 v[88:91], v249 offset:0
	ds_read_b128 v[92:95], v249 offset:4096
	ds_read_b128 v[96:99], v249 offset:8192
	ds_read_b128 v[100:103], v249 offset:12288
	ds_read_b128 v[104:107], v249 offset:16384
	ds_read_b128 v[108:111], v249 offset:20480
	ds_read_b128 v[112:115], v249 offset:24576
	ds_read_b128 v[116:119], v249 offset:28672
	ds_read_b128 v[120:123], v249 offset:32768
	s_waitcnt lgkmcnt(8)
	v_add_f32_e32 v0, v0, v88
	v_add_f32_e32 v1, v1, v89
	v_add_f32_e32 v2, v2, v90
	v_add_f32_e32 v3, v3, v91
	ds_read_b128 v[124:127], v249 offset:36864
	s_waitcnt lgkmcnt(8)
	v_add_f32_e32 v4, v4, v92
	v_add_f32_e32 v5, v5, v93
	v_add_f32_e32 v6, v6, v94
	v_add_f32_e32 v7, v7, v95
	ds_read_b128 v[128:131], v249 offset:40960
	s_waitcnt lgkmcnt(8)
	v_add_f32_e32 v8, v8, v96
	v_add_f32_e32 v9, v9, v97
	v_add_f32_e32 v10, v10, v98
	v_add_f32_e32 v11, v11, v99
	ds_read_b128 v[132:135], v249 offset:45056
	s_waitcnt lgkmcnt(8)
	v_add_f32_e32 v12, v12, v100
	v_add_f32_e32 v13, v13, v101
	v_add_f32_e32 v14, v14, v102
	v_add_f32_e32 v15, v15, v103
	ds_read_b128 v[136:139], v249 offset:49152
	s_waitcnt lgkmcnt(8)
	v_add_f32_e32 v16, v16, v104
	v_add_f32_e32 v17, v17, v105
	v_add_f32_e32 v18, v18, v106
	v_add_f32_e32 v19, v19, v107
	ds_read_b128 v[140:143], v249 offset:53248
	s_waitcnt lgkmcnt(8)
	v_add_f32_e32 v20, v20, v108
	v_add_f32_e32 v21, v21, v109
	v_add_f32_e32 v22, v22, v110
	v_add_f32_e32 v23, v23, v111
	ds_read_b128 v[144:147], v249 offset:57344
	s_waitcnt lgkmcnt(8)
	v_add_f32_e32 v24, v24, v112
	v_add_f32_e32 v25, v25, v113
	v_add_f32_e32 v26, v26, v114
	v_add_f32_e32 v27, v27, v115
	ds_read_b128 v[148:151], v249 offset:61440
	s_waitcnt lgkmcnt(8)
	v_add_f32_e32 v28, v28, v116
	v_add_f32_e32 v29, v29, v117
	v_add_f32_e32 v30, v30, v118
	v_add_f32_e32 v31, v31, v119
	s_waitcnt lgkmcnt(7)
	v_add_f32_e32 v32, v32, v120
	v_add_f32_e32 v33, v33, v121
	v_add_f32_e32 v34, v34, v122
	v_add_f32_e32 v35, v35, v123
	s_waitcnt lgkmcnt(6)
	v_add_f32_e32 v36, v36, v124
	v_add_f32_e32 v37, v37, v125
	v_add_f32_e32 v38, v38, v126
	v_add_f32_e32 v39, v39, v127
	s_waitcnt lgkmcnt(5)
	v_add_f32_e32 v40, v40, v128
	v_add_f32_e32 v41, v41, v129
	v_add_f32_e32 v42, v42, v130
	v_add_f32_e32 v43, v43, v131
	s_waitcnt lgkmcnt(4)
	v_add_f32_e32 v44, v44, v132
	v_add_f32_e32 v45, v45, v133
	v_add_f32_e32 v46, v46, v134
	v_add_f32_e32 v47, v47, v135
	s_waitcnt lgkmcnt(3)
	v_add_f32_e32 v48, v48, v136
	v_add_f32_e32 v49, v49, v137
	v_add_f32_e32 v50, v50, v138
	v_add_f32_e32 v51, v51, v139
	s_waitcnt lgkmcnt(2)
	v_add_f32_e32 v52, v52, v140
	v_add_f32_e32 v53, v53, v141
	v_add_f32_e32 v54, v54, v142
	v_add_f32_e32 v55, v55, v143
	s_waitcnt lgkmcnt(1)
	v_add_f32_e32 v56, v56, v144
	v_add_f32_e32 v57, v57, v145
	v_add_f32_e32 v58, v58, v146
	v_add_f32_e32 v59, v59, v147
	s_waitcnt lgkmcnt(0)
	v_add_f32_e32 v60, v60, v148
	v_add_f32_e32 v61, v61, v149
	v_add_f32_e32 v62, v62, v150
	v_add_f32_e32 v63, v63, v151

; DI f32x16 zero16() { f32x16 z; for (int i = 0; i < 16; ++i) z[i] = 0.f; return z; }
; DI void hy_conv(f32x16 (&acc)[4], const u16* abase, const u16* U, const u16* Zrow, int a0, int li, int g) {
; #pragma unroll
;   for (int i = 0; i < 4; ++i) acc[i] = zero16();
;   u32x4 W[14];
;   bf16x8 bf[8];
;   int d = a0 - 63;
; #pragma unroll
;   for (int x = 0; x < 14; ++x) W[x] = hy_afrag(abase, 8 * d + x - 7);
; DI void hyena_item(const P& p, int l, int c, char* smem) {
;     ...
;   hy_load_table(tbg + (size_t)512 * 16384, TbE, TbO, tid);
;   __syncthreads();
;   if (cwv) hy_conv(acc, abase, U, Zrow, a0, li, g);
.LBB0_455:
	s_or_b64 exec, exec, s[8:9]
	s_waitcnt vmcnt(0)
	ds_write_b128 v221, v[0:3] offset:24576
	v_perm_b32 v0, v0, v1, s68
	v_perm_b32 v1, v1, v2, s68
	v_perm_b32 v2, v2, v3, s68
	v_or_b32_sdwa v3, v6, v3 dst_sel:DWORD dst_unused:UNUSED_PAD src0_sel:DWORD src1_sel:WORD_1
	s_mov_b64 s[10:11], 0
	s_mov_b64 s[8:9], 0
	ds_write_b128 v221, v[0:3] offset:57408
	s_waitcnt lgkmcnt(0)
	s_barrier
	s_mov_b64 s[12:13], exec
	v_mov_b32_e32 v234, v228
	v_add_u32_e32 v242, 0xffffff40, v225
	v_lshlrev_b32_e32 v241, 8, v234
	v_sub_u32_e32 v240, v242, v241
	ds_read2_b32 v[72:73], v240 offset0:104 offset1:105
	ds_read2_b32 v[74:75], v240 offset0:106 offset1:107
	ds_read2_b32 v[76:77], v240 offset0:96 offset1:97
	ds_read2_b32 v[78:79], v240 offset0:98 offset1:99
	ds_read2_b32 v[80:81], v240 offset0:88 offset1:89
	ds_read2_b32 v[82:83], v240 offset0:90 offset1:91
	ds_read2_b32 v[84:85], v240 offset0:80 offset1:81
	ds_read2_b32 v[86:87], v240 offset0:82 offset1:83
	ds_read2_b32 v[88:89], v240 offset0:72 offset1:73
	ds_read2_b32 v[90:91], v240 offset0:74 offset1:75
	ds_read2_b32 v[92:93], v240 offset0:64 offset1:65
	ds_read2_b32 v[94:95], v240 offset0:66 offset1:67
	ds_read2_b32 v[96:97], v240 offset0:56 offset1:57
	ds_read2_b32 v[98:99], v240 offset0:58 offset1:59
	ds_read2_b32 v[100:101], v240 offset0:48 offset1:49
	ds_read2_b32 v[102:103], v240 offset0:50 offset1:51
	ds_read2_b32 v[104:105], v240 offset0:40 offset1:41
	ds_read2_b32 v[106:107], v240 offset0:42 offset1:43
	ds_read2_b32 v[108:109], v240 offset0:32 offset1:33
	ds_read2_b32 v[110:111], v240 offset0:34 offset1:35
	ds_read2_b32 v[112:113], v240 offset0:24 offset1:25
	ds_read2_b32 v[114:115], v240 offset0:26 offset1:27
	ds_read2_b32 v[116:117], v240 offset0:16 offset1:17
	ds_read2_b32 v[118:119], v240 offset0:18 offset1:19
	ds_read2_b32 v[120:121], v240 offset0:8 offset1:9
	ds_read2_b32 v[122:123], v240 offset0:10 offset1:11
	ds_read2_b32 v[124:125], v240 offset0:0 offset1:1
	ds_read2_b32 v[126:127], v240 offset0:2 offset1:3
	v_add_u32_e32 v241, v229, v224
	v_sub_u32_e32 v241, v241, v234
	v_mov_b32_e32 v244, s69
	v_mad_u32_u24 v236, v241, s97, v244
	v_add_u32_e32 v236, v236, v222
	v_sub_u32_e32 v235, v229, v234
	s_mov_b32 s99, 0x18880
	v_add_u32_e32 v243, s99, v222
	v_cmp_gt_u32_e32 vcc, 64, v235
	s_movk_i32 s98, 13
	v_mov_b32_e32 v0, 0
	v_cndmask_b32_e32 v237, v243, v236, vcc
	ds_read_b128 v[168:171], v237 offset:0
	ds_read_b128 v[172:175], v237 offset:32
	ds_read_b128 v[176:179], v237 offset:64
	ds_read_b128 v[180:183], v237 offset:96
	v_mov_b32_e32 v1, v0
	v_mov_b32_e32 v2, v0
	v_mov_b32_e32 v3, v0
	v_mov_b32_e32 v4, v0
	v_mov_b32_e32 v5, v0
	v_mov_b32_e32 v6, v0
	v_mov_b32_e32 v7, v0
	v_mov_b32_e32 v8, v0
	v_mov_b32_e32 v9, v0
	v_mov_b32_e32 v10, v0
	v_mov_b32_e32 v11, v0
	v_mov_b32_e32 v12, v0
	v_mov_b32_e32 v13, v0
	v_mov_b32_e32 v14, v0
	v_mov_b32_e32 v15, v0
	v_mov_b32_e32 v16, v0
	v_mov_b32_e32 v17, v0
	v_mov_b32_e32 v18, v0
	v_mov_b32_e32 v19, v0
	v_mov_b32_e32 v20, v0
	v_mov_b32_e32 v21, v0
	v_mov_b32_e32 v22, v0
	v_mov_b32_e32 v23, v0
	v_mov_b32_e32 v24, v0
	v_mov_b32_e32 v25, v0
	v_mov_b32_e32 v26, v0
	v_mov_b32_e32 v27, v0
	v_mov_b32_e32 v28, v0
	v_mov_b32_e32 v29, v0
	v_mov_b32_e32 v30, v0
	v_mov_b32_e32 v31, v0
	v_mov_b32_e32 v32, v0
	v_mov_b32_e32 v33, v0
	v_mov_b32_e32 v34, v0
	v_mov_b32_e32 v35, v0
	v_mov_b32_e32 v36, v0
	v_mov_b32_e32 v37, v0
	v_mov_b32_e32 v38, v0
	v_mov_b32_e32 v39, v0
	v_mov_b32_e32 v40, v0
	v_mov_b32_e32 v41, v0
	v_mov_b32_e32 v42, v0
	v_mov_b32_e32 v43, v0
	v_mov_b32_e32 v44, v0
	v_mov_b32_e32 v45, v0
	v_mov_b32_e32 v46, v0
	v_mov_b32_e32 v47, v0
	v_mov_b32_e32 v48, v0
	v_mov_b32_e32 v49, v0
	v_mov_b32_e32 v50, v0
	v_mov_b32_e32 v51, v0
	v_mov_b32_e32 v52, v0
	v_mov_b32_e32 v53, v0
	v_mov_b32_e32 v54, v0
	v_mov_b32_e32 v55, v0
	v_mov_b32_e32 v56, v0
	v_mov_b32_e32 v57, v0
	v_mov_b32_e32 v58, v0
	v_mov_b32_e32 v59, v0
	v_mov_b32_e32 v60, v0
	v_mov_b32_e32 v61, v0
	v_mov_b32_e32 v62, v0
	v_mov_b32_e32 v63, v0
	s_waitcnt lgkmcnt(0)

; DI void hyena_item(const P& p, int l, int c, char* smem) {
;     ...
;   if (cwv) hy_conv(acc, abase, U, Zrow, a0, li, g);
;   if (cwv) {
;     const float d1 = p.fbias[(size_t)(l * 2 + 1) * 512 + c];
;     const float x0 = cw[1024 + c], x1 = cw[1536 + 1024 + c], x2 = cw[3072 + 1024 + c], xb = cbias[1024 + c];
;     const u16* rowx = p.hyT + (size_t)(1024 + c) * HYP + bt * SEQ;
;     const u16* rowg = p.hyT + (size_t)(1536 + c) * HYP + bt * SEQ;
;     u16* dst = p.YhT + (size_t)c * HYP + bt * SEQ;
; #pragma unroll
;     for (int I = 0; I < 4; ++I)
; #pragma unroll
;       for (int rq = 0; rq < 4; ++rq) {
;         const int bq = 32 * I + 8 * rq + 4 * g;
;         const int t4 = 128 * a + bq;
;         float px[4];
;         sconv4(rowx, t4, x0, x1, x2, xb, px);
;         const uint2 zv = *(const uint2*)(U + (bt * 64 + a) * 136 + bq);
;         const uint2 gv = *(const uint2*)(rowg + t4);
.Lhc1_done:
	v_readlane_b32 s6, v248, 24
	s_nop 1
	s_add_i32 s6, s72, s6
	s_mov_b32 s7, s57
	s_lshl_b64 s[6:7], s[6:7], 2
	s_add_u32 s6, s20, s6
	s_addc_u32 s7, s21, s7
	s_or_b32 s8, s72, 0x400
	s_mov_b32 s9, s57
	s_lshl_b64 s[14:15], s[8:9], 2
	s_add_u32 s76, s28, s14
	s_addc_u32 s77, s29, s15
	v_readlane_b32 s9, v248, 28
	s_nop 1
	s_add_u32 s14, s9, s14
	v_readlane_b32 s9, v248, 29
	s_nop 1
	s_addc_u32 s15, s9, s15
	s_waitcnt lgkmcnt(0)
	s_barrier
	v_and_b32_e32 v249, 0xff, v198
	v_lshlrev_b32_e32 v249, 4, v249
	v_cmp_lt_i32_e32 vcc, 0, v250
	s_cbranch_vccnz .Lhy1_rd_main
	s_nop 15
	ds_write_b128 v249, v[0:3] offset:0
	ds_write_b128 v249, v[4:7] offset:4096
	ds_write_b128 v249, v[8:11] offset:8192
	ds_write_b128 v249, v[12:15] offset:12288
	ds_write_b128 v249, v[16:19] offset:16384
	ds_write_b128 v249, v[20:23] offset:20480
	ds_write_b128 v249, v[24:27] offset:24576
	ds_write_b128 v249, v[28:31] offset:28672
	ds_write_b128 v249, v[32:35] offset:32768
	ds_write_b128 v249, v[36:39] offset:36864
	ds_write_b128 v249, v[40:43] offset:40960
	ds_write_b128 v249, v[44:47] offset:45056
	ds_write_b128 v249, v[48:51] offset:49152
	ds_write_b128 v249, v[52:55] offset:53248
	ds_write_b128 v249, v[56:59] offset:57344
	ds_write_b128 v249, v[60:63] offset:61440
	s_waitcnt lgkmcnt(0)
.Lhy1_rd_main:
	s_barrier
	v_cmp_lt_i32_e32 vcc, 0, v250
	s_cbranch_vccz .Lhy1_skip
	ds_read_b128 v[88:91], v249 offset:0
	ds_read_b128 v[92:95], v249 offset:4096
	ds_read_b128 v[96:99], v249 offset:8192
	ds_read_b128 v[100:103], v249 offset:12288
	ds_read_b128 v[104:107], v249 offset:16384
	ds_read_b128 v[108:111], v249 offset:20480
	ds_read_b128 v[112:115], v249 offset:24576
	ds_read_b128 v[116:119], v249 offset:28672
	ds_read_b128 v[120:123], v249 offset:32768
	s_waitcnt lgkmcnt(8)
	v_add_f32_e32 v0, v0, v88
	v_add_f32_e32 v1, v1, v89
	v_add_f32_e32 v2, v2, v90
	v_add_f32_e32 v3, v3, v91
	ds_read_b128 v[124:127], v249 offset:36864
	s_waitcnt lgkmcnt(8)
	v_add_f32_e32 v4, v4, v92
	v_add_f32_e32 v5, v5, v93
	v_add_f32_e32 v6, v6, v94
	v_add_f32_e32 v7, v7, v95
	ds_read_b128 v[128:131], v249 offset:40960
	s_waitcnt lgkmcnt(8)
	v_add_f32_e32 v8, v8, v96
	v_add_f32_e32 v9, v9, v97
	v_add_f32_e32 v10, v10, v98
	v_add_f32_e32 v11, v11, v99
	ds_read_b128 v[132:135], v249 offset:45056
	s_waitcnt lgkmcnt(8)
	v_add_f32_e32 v12, v12, v100
	v_add_f32_e32 v13, v13, v101
	v_add_f32_e32 v14, v14, v102
	v_add_f32_e32 v15, v15, v103
	ds_read_b128 v[136:139], v249 offset:49152
	s_waitcnt lgkmcnt(8)
	v_add_f32_e32 v16, v16, v104
	v_add_f32_e32 v17, v17, v105
	v_add_f32_e32 v18, v18, v106
	v_add_f32_e32 v19, v19, v107
	ds_read_b128 v[140:143], v249 offset:53248
	s_waitcnt lgkmcnt(8)
	v_add_f32_e32 v20, v20, v108
	v_add_f32_e32 v21, v21, v109
	v_add_f32_e32 v22, v22, v110
	v_add_f32_e32 v23, v23, v111
	ds_read_b128 v[144:147], v249 offset:57344
	s_waitcnt lgkmcnt(8)
	v_add_f32_e32 v24, v24, v112
	v_add_f32_e32 v25, v25, v113
	v_add_f32_e32 v26, v26, v114
	v_add_f32_e32 v27, v27, v115
	ds_read_b128 v[148:151], v249 offset:61440
	s_waitcnt lgkmcnt(8)
	v_add_f32_e32 v28, v28, v116
	v_add_f32_e32 v29, v29, v117
	v_add_f32_e32 v30, v30, v118
	v_add_f32_e32 v31, v31, v119
	s_waitcnt lgkmcnt(7)
	v_add_f32_e32 v32, v32, v120
	v_add_f32_e32 v33, v33, v121
	v_add_f32_e32 v34, v34, v122
	v_add_f32_e32 v35, v35, v123
	s_waitcnt lgkmcnt(6)
	v_add_f32_e32 v36, v36, v124
	v_add_f32_e32 v37, v37, v125
	v_add_f32_e32 v38, v38, v126
	v_add_f32_e32 v39, v39, v127
	s_waitcnt lgkmcnt(5)
	v_add_f32_e32 v40, v40, v128
	v_add_f32_e32 v41, v41, v129
	v_add_f32_e32 v42, v42, v130
	v_add_f32_e32 v43, v43, v131
	s_waitcnt lgkmcnt(4)
	v_add_f32_e32 v44, v44, v132
	v_add_f32_e32 v45, v45, v133
	v_add_f32_e32 v46, v46, v134
	v_add_f32_e32 v47, v47, v135
	s_waitcnt lgkmcnt(3)
	v_add_f32_e32 v48, v48, v136
	v_add_f32_e32 v49, v49, v137
	v_add_f32_e32 v50, v50, v138
	v_add_f32_e32 v51, v51, v139
	s_waitcnt lgkmcnt(2)
	v_add_f32_e32 v52, v52, v140
	v_add_f32_e32 v53, v53, v141
	v_add_f32_e32 v54, v54, v142
	v_add_f32_e32 v55, v55, v143
	s_waitcnt lgkmcnt(1)
	v_add_f32_e32 v56, v56, v144
	v_add_f32_e32 v57, v57, v145
	v_add_f32_e32 v58, v58, v146
	v_add_f32_e32 v59, v59, v147
	s_waitcnt lgkmcnt(0)
	v_add_f32_e32 v60, v60, v148
	v_add_f32_e32 v61, v61, v149
	v_add_f32_e32 v62, v62, v150
	v_add_f32_e32 v63, v63, v151
	global_load_dword v82, v204, s[74:75] offset:2048
	global_load_dword v80, v207, s[74:75]
	global_load_dword v68, v189, s[6:7] offset:2048
	global_load_dword v83, v189, s[76:77]
	global_load_dword v70, v189, s[14:15]
	s_or_b32 s98, s72, 0x400
	s_mul_hi_u32 s99, s98, 0x8080
	s_mul_i32 s98, s98, 0x8080
	s_add_u32 s98, s36, s98
	s_addc_u32 s99, s37, s99
	s_add_u32 s98, s98, -4
	s_addc_u32 s99, s99, -1
	s_or_b32 s100, s72, 0x600
	s_mul_hi_u32 s101, s100, 0x8080
	s_mul_i32 s100, s100, 0x8080
	s_add_u32 s100, s36, s100
	s_addc_u32 s101, s37, s101
	s_add_u32 s6, s48, s96
	s_addc_u32 s7, s49, s73
	v_lshl_add_u32 v234, v233, 1, v184
	global_load_dwordx4 v[88:91], v234, s[98:99] offset:0
	global_load_dwordx2 v[92:93], v234, s[100:101] offset:0
	global_load_dwordx4 v[94:97], v234, s[98:99] offset:16
	global_load_dwordx2 v[98:99], v234, s[100:101] offset:16
	global_load_dwordx4 v[100:103], v234, s[98:99] offset:32
	global_load_dwordx2 v[104:105], v234, s[100:101] offset:32
	global_load_dwordx4 v[106:109], v234, s[98:99] offset:48
	global_load_dwordx2 v[110:111], v234, s[100:101] offset:48
	global_load_dwordx4 v[112:115], v234, s[98:99] offset:64
	global_load_dwordx2 v[116:117], v234, s[100:101] offset:64
	global_load_dwordx4 v[118:121], v234, s[98:99] offset:80
	global_load_dwordx2 v[122:123], v234, s[100:101] offset:80
	global_load_dwordx4 v[124:127], v234, s[98:99] offset:96
	global_load_dwordx2 v[128:129], v234, s[100:101] offset:96
	global_load_dwordx4 v[130:133], v234, s[98:99] offset:112
	global_load_dwordx2 v[134:135], v234, s[100:101] offset:112
	v_add_f32_e32 v238, v64, v65
	v_add_f32_e32 v238, v238, v66
	v_add_f32_e32 v238, v238, v67
	v_div_scale_f32 v169, s[8:9], v238, v238, 1.0
	v_rcp_f32_e32 v170, v169
	s_nop 0
	v_fma_f32 v171, -v169, v170, 1.0
	v_fmac_f32_e32 v170, v171, v170
	v_div_scale_f32 v171, vcc, 1.0, v238, 1.0
	v_mul_f32_e32 v236, v171, v170
	v_fma_f32 v237, -v169, v236, v171
	v_fmac_f32_e32 v236, v237, v170
	v_fma_f32 v169, -v169, v236, v171
	v_div_fmas_f32 v169, v169, v170, v236
	v_div_fixup_f32 v238, v169, v238, 1.0
	v_lshl_or_b32 v235, v230, 6, v231
	v_mul_u32_u24_e32 v235, 0x110, v235
	v_lshlrev_b32_e32 v236, 1, v186
	v_add3_u32 v235, s69, v235, v236
	s_waitcnt vmcnt(8)
; DI float bf2f(unsigned v) { return __uint_as_float(v << 16); }
; DI float bflo(unsigned v) { return __uint_as_float(v << 16); }
; DI float bfhi(unsigned v) { return __uint_as_float(v & 0xffff0000u); }
; DI float siluf(float x) { return x * __builtin_amdgcn_rcpf(1.f + __expf(-x)); }
; DI void sconv4(const u16* row, int t4, float w0, float w1, float w2, float bias, float (&o)[4]) {
;   const uint2 v = *(const uint2*)(row + t4);
;   const float x0 = bflo(v.x), x1 = bfhi(v.x), x2 = bflo(v.y), x3 = bfhi(v.y);
;   const float xm = (t4 > 0) ? bf2f(row[t4 - 1]) : 0.f;
;   const float xp = (t4 + 4 < SEQ) ? bf2f(row[t4 + 4]) : 0.f;
;   o[0] = w0 * xm + w1 * x0 + w2 * x1 + bias;
;   o[1] = w0 * x0 + w1 * x1 + w2 * x2 + bias;
;   o[2] = w0 * x1 + w1 * x2 + w2 * x3 + bias;
;   o[3] = w0 * x2 + w1 * x3 + w2 * xp + bias;
; }
; DI void hyena_item(const P& p, int l, int c, char* smem) {
;     ...
;       for (int rq = 0; rq < 4; ++rq) {
;         const int bq = 32 * I + 8 * rq + 4 * g;
;         const int t4 = 128 * a + bq;
;         float px[4];
;         sconv4(rowx, t4, x0, x1, x2, xb, px);
;         const uint2 zv = *(const uint2*)(U + (bt * 64 + a) * 136 + bq);
;         const uint2 gv = *(const uint2*)(rowg + t4);
;         const float z1[4] = {bflo(zv.x), bfhi(zv.x), bflo(zv.y), bfhi(zv.y)};
;         const float gt[4] = {bflo(gv.x), bfhi(gv.x), bflo(gv.y), bfhi(gv.y)};
;         float yy[4];
; #pragma unroll
;         for (int j = 0; j < 4; ++j) yy[j] = px[j] * (acc[I][4 * rq + j] * invn1 + z1[j] * d1) * siluf(gt[j]);
;         uint2 ov; ov.x = pack2(yy[0], yy[1]); ov.y = pack2(yy[2], yy[3]);
;         *(uint2*)(dst + t4) = ov;
;       }
	ds_read_b64 v[160:161], v235 offset:0
	ds_read_b64 v[162:163], v235 offset:16
	ds_read_b64 v[164:165], v235 offset:32
	ds_read_b64 v[166:167], v235 offset:48
	v_cmp_ne_u32_e32 vcc, 0, v233
	s_nop 1
	v_and_b32_e32 v168, 0xffff0000, v88
	v_cndmask_b32_e32 v168, 0, v168, vcc
	v_lshlrev_b32_e32 v169, 16, v89
	v_and_b32_e32 v170, 0xffff0000, v89
	v_lshlrev_b32_e32 v171, 16, v90
	v_and_b32_e32 v172, 0xffff0000, v90
	v_lshlrev_b32_e32 v173, 16, v91
	v_mul_f32_e32 v178, v83, v168
	v_fmac_f32_e32 v178, v82, v169
	v_fmac_f32_e32 v178, v80, v170
	v_add_f32_e32 v178, v70, v178
	v_mul_f32_e32 v179, v83, v169
	v_fmac_f32_e32 v179, v82, v170
	v_fmac_f32_e32 v179, v80, v171
	v_add_f32_e32 v179, v70, v179
	v_mul_f32_e32 v180, v83, v170
	v_fmac_f32_e32 v180, v82, v171
	v_fmac_f32_e32 v180, v80, v172
	v_add_f32_e32 v180, v70, v180
	v_mul_f32_e32 v181, v83, v171
	v_fmac_f32_e32 v181, v82, v172
	v_fmac_f32_e32 v181, v80, v173
	v_add_f32_e32 v181, v70, v181
	s_waitcnt lgkmcnt(0)
	v_lshlrev_b32_e32 v174, 16, v160
	v_and_b32_e32 v175, 0xffff0000, v160
	v_lshlrev_b32_e32 v176, 16, v161
	v_and_b32_e32 v177, 0xffff0000, v161
	v_mul_f32_e32 v174, v68, v174
	v_mul_f32_e32 v175, v68, v175
	v_mul_f32_e32 v176, v68, v176
	v_mul_f32_e32 v177, v68, v177
	v_fmac_f32_e32 v174, v238, v48
	v_fmac_f32_e32 v175, v238, v49
	v_fmac_f32_e32 v176, v238, v50
	v_fmac_f32_e32 v177, v238, v51
	v_mul_f32_e32 v174, v178, v174
	v_mul_f32_e32 v175, v179, v175
	v_mul_f32_e32 v176, v180, v176
	v_mul_f32_e32 v177, v181, v177
	v_lshlrev_b32_e32 v168, 16, v92
	v_and_b32_e32 v169, 0xffff0000, v92
	v_lshlrev_b32_e32 v170, 16, v93
	v_and_b32_e32 v171, 0xffff0000, v93
	v_mul_f32_e32 v178, 0xbfb8aa3b, v168
	v_mul_f32_e32 v179, 0xbfb8aa3b, v169
	v_mul_f32_e32 v180, 0xbfb8aa3b, v170
	v_mul_f32_e32 v181, 0xbfb8aa3b, v171
	v_exp_f32_e32 v178, v178
	v_exp_f32_e32 v179, v179
	v_exp_f32_e32 v180, v180
	v_exp_f32_e32 v181, v181
	v_add_f32_e32 v178, 1.0, v178
	v_add_f32_e32 v179, 1.0, v179
	v_add_f32_e32 v180, 1.0, v180
	v_add_f32_e32 v181, 1.0, v181
	v_rcp_f32_e32 v178, v178
	v_rcp_f32_e32 v179, v179
	v_rcp_f32_e32 v180, v180
	v_rcp_f32_e32 v181, v181
	v_mul_f32_e32 v178, v178, v168
	v_mul_f32_e32 v179, v179, v169
	v_mul_f32_e32 v180, v180, v170
	v_mul_f32_e32 v181, v181, v171
	v_mul_f32_e32 v174, v174, v178
	v_mul_f32_e32 v175, v175, v179
	v_mul_f32_e32 v176, v176, v180
	v_mul_f32_e32 v177, v177, v181
	v_cvt_pk_bf16_f32 v182, v174, v175
	v_cvt_pk_bf16_f32 v183, v176, v177
	global_store_dwordx2 v234, v[182:183], s[6:7] offset:0
	v_and_b32_e32 v168, 0xffff0000, v94
	v_lshlrev_b32_e32 v169, 16, v95
	v_and_b32_e32 v170, 0xffff0000, v95
	v_lshlrev_b32_e32 v171, 16, v96
	v_and_b32_e32 v172, 0xffff0000, v96
	v_lshlrev_b32_e32 v173, 16, v97
	v_mul_f32_e32 v178, v83, v168
	v_fmac_f32_e32 v178, v82, v169
	v_fmac_f32_e32 v178, v80, v170
	v_add_f32_e32 v178, v70, v178
	v_mul_f32_e32 v179, v83, v169
	v_fmac_f32_e32 v179, v82, v170
	v_fmac_f32_e32 v179, v80, v171
	v_add_f32_e32 v179, v70, v179
	v_mul_f32_e32 v180, v83, v170
	v_fmac_f32_e32 v180, v82, v171
	v_fmac_f32_e32 v180, v80, v172
	v_add_f32_e32 v180, v70, v180
	v_mul_f32_e32 v181, v83, v171
	v_fmac_f32_e32 v181, v82, v172
	v_fmac_f32_e32 v181, v80, v173
	v_add_f32_e32 v181, v70, v181
	v_lshlrev_b32_e32 v174, 16, v162
	v_and_b32_e32 v175, 0xffff0000, v162
	v_lshlrev_b32_e32 v176, 16, v163
	v_and_b32_e32 v177, 0xffff0000, v163
	v_mul_f32_e32 v174, v68, v174
	v_mul_f32_e32 v175, v68, v175
	v_mul_f32_e32 v176, v68, v176
	v_mul_f32_e32 v177, v68, v177
	v_fmac_f32_e32 v174, v238, v52
	v_fmac_f32_e32 v175, v238, v53
	v_fmac_f32_e32 v176, v238, v54
	v_fmac_f32_e32 v177, v238, v55
	v_mul_f32_e32 v174, v178, v174
	v_mul_f32_e32 v175, v179, v175
	v_mul_f32_e32 v176, v180, v176
	v_mul_f32_e32 v177, v181, v177
	v_lshlrev_b32_e32 v168, 16, v98
	v_and_b32_e32 v169, 0xffff0000, v98
	v_lshlrev_b32_e32 v170, 16, v99
	v_and_b32_e32 v171, 0xffff0000, v99
	v_mul_f32_e32 v178, 0xbfb8aa3b, v168
	v_mul_f32_e32 v179, 0xbfb8aa3b, v169
	v_mul_f32_e32 v180, 0xbfb8aa3b, v170
	v_mul_f32_e32 v181, 0xbfb8aa3b, v171
	v_exp_f32_e32 v178, v178
	v_exp_f32_e32 v179, v179
	v_exp_f32_e32 v180, v180
	v_exp_f32_e32 v181, v181
	v_add_f32_e32 v178, 1.0, v178
	v_add_f32_e32 v179, 1.0, v179
	v_add_f32_e32 v180, 1.0, v180
	v_add_f32_e32 v181, 1.0, v181
	v_rcp_f32_e32 v178, v178
	v_rcp_f32_e32 v179, v179
	v_rcp_f32_e32 v180, v180
	v_rcp_f32_e32 v181, v181
	v_mul_f32_e32 v178, v178, v168
	v_mul_f32_e32 v179, v179, v169
	v_mul_f32_e32 v180, v180, v170
	v_mul_f32_e32 v181, v181, v171
	v_mul_f32_e32 v174, v174, v178
	v_mul_f32_e32 v175, v175, v179
	v_mul_f32_e32 v176, v176, v180
	v_mul_f32_e32 v177, v177, v181
	v_cvt_pk_bf16_f32 v182, v174, v175
	v_cvt_pk_bf16_f32 v183, v176, v177
	global_store_dwordx2 v234, v[182:183], s[6:7] offset:16
	v_and_b32_e32 v168, 0xffff0000, v100
	v_lshlrev_b32_e32 v169, 16, v101
	v_and_b32_e32 v170, 0xffff0000, v101
	v_lshlrev_b32_e32 v171, 16, v102
	v_and_b32_e32 v172, 0xffff0000, v102
	v_lshlrev_b32_e32 v173, 16, v103
	v_mul_f32_e32 v178, v83, v168
	v_fmac_f32_e32 v178, v82, v169
	v_fmac_f32_e32 v178, v80, v170
	v_add_f32_e32 v178, v70, v178
	v_mul_f32_e32 v179, v83, v169
	v_fmac_f32_e32 v179, v82, v170
	v_fmac_f32_e32 v179, v80, v171
	v_add_f32_e32 v179, v70, v179
	v_mul_f32_e32 v180, v83, v170
	v_fmac_f32_e32 v180, v82, v171
	v_fmac_f32_e32 v180, v80, v172
	v_add_f32_e32 v180, v70, v180
	v_mul_f32_e32 v181, v83, v171
	v_fmac_f32_e32 v181, v82, v172
	v_fmac_f32_e32 v181, v80, v173
	v_add_f32_e32 v181, v70, v181
	v_lshlrev_b32_e32 v174, 16, v164
	v_and_b32_e32 v175, 0xffff0000, v164
	v_lshlrev_b32_e32 v176, 16, v165
	v_and_b32_e32 v177, 0xffff0000, v165
	v_mul_f32_e32 v174, v68, v174
; DI float bf2f(unsigned v) { return __uint_as_float(v << 16); }
; DI float bflo(unsigned v) { return __uint_as_float(v << 16); }
; DI float bfhi(unsigned v) { return __uint_as_float(v & 0xffff0000u); }
; DI float siluf(float x) { return x * __builtin_amdgcn_rcpf(1.f + __expf(-x)); }
; DI void sconv4(const u16* row, int t4, float w0, float w1, float w2, float bias, float (&o)[4]) {
;   const uint2 v = *(const uint2*)(row + t4);
;   const float x0 = bflo(v.x), x1 = bfhi(v.x), x2 = bflo(v.y), x3 = bfhi(v.y);
;   const float xm = (t4 > 0) ? bf2f(row[t4 - 1]) : 0.f;
;   const float xp = (t4 + 4 < SEQ) ? bf2f(row[t4 + 4]) : 0.f;
;   o[0] = w0 * xm + w1 * x0 + w2 * x1 + bias;
;   o[1] = w0 * x0 + w1 * x1 + w2 * x2 + bias;
;   o[2] = w0 * x1 + w1 * x2 + w2 * x3 + bias;
;   o[3] = w0 * x2 + w1 * x3 + w2 * xp + bias;
; }
; DI void hyena_item(const P& p, int l, int c, char* smem) {
;     ...
;       for (int rq = 0; rq < 4; ++rq) {
;         const int bq = 32 * I + 8 * rq + 4 * g;
;         const int t4 = 128 * a + bq;
;         float px[4];
;         sconv4(rowx, t4, x0, x1, x2, xb, px);
;         const uint2 zv = *(const uint2*)(U + (bt * 64 + a) * 136 + bq);
;         const uint2 gv = *(const uint2*)(rowg + t4);
;         const float z1[4] = {bflo(zv.x), bfhi(zv.x), bflo(zv.y), bfhi(zv.y)};
;         const float gt[4] = {bflo(gv.x), bfhi(gv.x), bflo(gv.y), bfhi(gv.y)};
;         float yy[4];
; #pragma unroll
;         for (int j = 0; j < 4; ++j) yy[j] = px[j] * (acc[I][4 * rq + j] * invn1 + z1[j] * d1) * siluf(gt[j]);
;         uint2 ov; ov.x = pack2(yy[0], yy[1]); ov.y = pack2(yy[2], yy[3]);
;         *(uint2*)(dst + t4) = ov;
;       }
	v_mul_f32_e32 v175, v68, v175
	v_mul_f32_e32 v176, v68, v176
	v_mul_f32_e32 v177, v68, v177
	v_fmac_f32_e32 v174, v238, v56
	v_fmac_f32_e32 v175, v238, v57
	v_fmac_f32_e32 v176, v238, v58
	v_fmac_f32_e32 v177, v238, v59
	v_mul_f32_e32 v174, v178, v174
	v_mul_f32_e32 v175, v179, v175
	v_mul_f32_e32 v176, v180, v176
	v_mul_f32_e32 v177, v181, v177
	v_lshlrev_b32_e32 v168, 16, v104
	v_and_b32_e32 v169, 0xffff0000, v104
	v_lshlrev_b32_e32 v170, 16, v105
	v_and_b32_e32 v171, 0xffff0000, v105
	v_mul_f32_e32 v178, 0xbfb8aa3b, v168
	v_mul_f32_e32 v179, 0xbfb8aa3b, v169
	v_mul_f32_e32 v180, 0xbfb8aa3b, v170
	v_mul_f32_e32 v181, 0xbfb8aa3b, v171
	v_exp_f32_e32 v178, v178
	v_exp_f32_e32 v179, v179
	v_exp_f32_e32 v180, v180
	v_exp_f32_e32 v181, v181
	v_add_f32_e32 v178, 1.0, v178
	v_add_f32_e32 v179, 1.0, v179
	v_add_f32_e32 v180, 1.0, v180
	v_add_f32_e32 v181, 1.0, v181
	v_rcp_f32_e32 v178, v178
	v_rcp_f32_e32 v179, v179
	v_rcp_f32_e32 v180, v180
	v_rcp_f32_e32 v181, v181
	v_mul_f32_e32 v178, v178, v168
	v_mul_f32_e32 v179, v179, v169
	v_mul_f32_e32 v180, v180, v170
	v_mul_f32_e32 v181, v181, v171
	v_mul_f32_e32 v174, v174, v178
	v_mul_f32_e32 v175, v175, v179
	v_mul_f32_e32 v176, v176, v180
	v_mul_f32_e32 v177, v177, v181
	v_cvt_pk_bf16_f32 v182, v174, v175
	v_cvt_pk_bf16_f32 v183, v176, v177
	global_store_dwordx2 v234, v[182:183], s[6:7] offset:32
	v_and_b32_e32 v168, 0xffff0000, v106
	v_lshlrev_b32_e32 v169, 16, v107
	v_and_b32_e32 v170, 0xffff0000, v107
	v_lshlrev_b32_e32 v171, 16, v108
	v_and_b32_e32 v172, 0xffff0000, v108
	v_lshlrev_b32_e32 v173, 16, v109
	v_mul_f32_e32 v178, v83, v168
	v_fmac_f32_e32 v178, v82, v169
	v_fmac_f32_e32 v178, v80, v170
	v_add_f32_e32 v178, v70, v178
	v_mul_f32_e32 v179, v83, v169
	v_fmac_f32_e32 v179, v82, v170
	v_fmac_f32_e32 v179, v80, v171
	v_add_f32_e32 v179, v70, v179
	v_mul_f32_e32 v180, v83, v170
	v_fmac_f32_e32 v180, v82, v171
	v_fmac_f32_e32 v180, v80, v172
	v_add_f32_e32 v180, v70, v180
	v_mul_f32_e32 v181, v83, v171
	v_fmac_f32_e32 v181, v82, v172
	v_fmac_f32_e32 v181, v80, v173
	v_add_f32_e32 v181, v70, v181
	v_lshlrev_b32_e32 v174, 16, v166
	v_and_b32_e32 v175, 0xffff0000, v166
	v_lshlrev_b32_e32 v176, 16, v167
	v_and_b32_e32 v177, 0xffff0000, v167
	v_mul_f32_e32 v174, v68, v174
	v_mul_f32_e32 v175, v68, v175
	v_mul_f32_e32 v176, v68, v176
	v_mul_f32_e32 v177, v68, v177
	v_fmac_f32_e32 v174, v238, v60
	v_fmac_f32_e32 v175, v238, v61
	v_fmac_f32_e32 v176, v238, v62
	v_fmac_f32_e32 v177, v238, v63
	v_mul_f32_e32 v174, v178, v174
	v_mul_f32_e32 v175, v179, v175
	v_mul_f32_e32 v176, v180, v176
	v_mul_f32_e32 v177, v181, v177
	v_lshlrev_b32_e32 v168, 16, v110
	v_and_b32_e32 v169, 0xffff0000, v110
	v_lshlrev_b32_e32 v170, 16, v111
	v_and_b32_e32 v171, 0xffff0000, v111
	v_mul_f32_e32 v178, 0xbfb8aa3b, v168
	v_mul_f32_e32 v179, 0xbfb8aa3b, v169
	v_mul_f32_e32 v180, 0xbfb8aa3b, v170
	v_mul_f32_e32 v181, 0xbfb8aa3b, v171
	v_exp_f32_e32 v178, v178
	v_exp_f32_e32 v179, v179
	v_exp_f32_e32 v180, v180
	v_exp_f32_e32 v181, v181
	v_add_f32_e32 v178, 1.0, v178
	v_add_f32_e32 v179, 1.0, v179
	v_add_f32_e32 v180, 1.0, v180
	v_add_f32_e32 v181, 1.0, v181
	v_rcp_f32_e32 v178, v178
	v_rcp_f32_e32 v179, v179
	v_rcp_f32_e32 v180, v180
	v_rcp_f32_e32 v181, v181
	v_mul_f32_e32 v178, v178, v168
	v_mul_f32_e32 v179, v179, v169
	v_mul_f32_e32 v180, v180, v170
	v_mul_f32_e32 v181, v181, v171
	v_mul_f32_e32 v174, v174, v178
	v_mul_f32_e32 v175, v175, v179
	v_mul_f32_e32 v176, v176, v180
	v_mul_f32_e32 v177, v177, v181
	v_cvt_pk_bf16_f32 v182, v174, v175
	v_cvt_pk_bf16_f32 v183, v176, v177
	global_store_dwordx2 v234, v[182:183], s[6:7] offset:48
	global_load_dwordx4 v[136:139], v234, s[98:99] offset:128
	global_load_dwordx2 v[140:141], v234, s[100:101] offset:128
	global_load_dwordx4 v[142:145], v234, s[98:99] offset:144
	global_load_dwordx2 v[146:147], v234, s[100:101] offset:144
	global_load_dwordx4 v[148:151], v234, s[98:99] offset:160
	global_load_dwordx2 v[152:153], v234, s[100:101] offset:160
	global_load_dwordx4 v[154:157], v234, s[98:99] offset:176
	global_load_dwordx2 v[158:159], v234, s[100:101] offset:176
	s_waitcnt vmcnt(12)
	ds_read_b64 v[160:161], v235 offset:64
	ds_read_b64 v[162:163], v235 offset:80
	ds_read_b64 v[164:165], v235 offset:96
	ds_read_b64 v[166:167], v235 offset:112
	v_and_b32_e32 v168, 0xffff0000, v112
	v_lshlrev_b32_e32 v169, 16, v113
	v_and_b32_e32 v170, 0xffff0000, v113
	v_lshlrev_b32_e32 v171, 16, v114
	v_and_b32_e32 v172, 0xffff0000, v114
	v_lshlrev_b32_e32 v173, 16, v115
	v_mul_f32_e32 v178, v83, v168
	v_fmac_f32_e32 v178, v82, v169
	v_fmac_f32_e32 v178, v80, v170
	v_add_f32_e32 v178, v70, v178
	v_mul_f32_e32 v179, v83, v169
	v_fmac_f32_e32 v179, v82, v170
	v_fmac_f32_e32 v179, v80, v171
	v_add_f32_e32 v179, v70, v179
	v_mul_f32_e32 v180, v83, v170
	v_fmac_f32_e32 v180, v82, v171
	v_fmac_f32_e32 v180, v80, v172
	v_add_f32_e32 v180, v70, v180
	v_mul_f32_e32 v181, v83, v171
	v_fmac_f32_e32 v181, v82, v172
	v_fmac_f32_e32 v181, v80, v173
	v_add_f32_e32 v181, v70, v181
	s_waitcnt lgkmcnt(0)
; DI float bf2f(unsigned v) { return __uint_as_float(v << 16); }
; DI float bflo(unsigned v) { return __uint_as_float(v << 16); }
; DI float bfhi(unsigned v) { return __uint_as_float(v & 0xffff0000u); }
; DI float siluf(float x) { return x * __builtin_amdgcn_rcpf(1.f + __expf(-x)); }
; DI void sconv4(const u16* row, int t4, float w0, float w1, float w2, float bias, float (&o)[4]) {
;   const uint2 v = *(const uint2*)(row + t4);
;   const float x0 = bflo(v.x), x1 = bfhi(v.x), x2 = bflo(v.y), x3 = bfhi(v.y);
;   const float xm = (t4 > 0) ? bf2f(row[t4 - 1]) : 0.f;
;   const float xp = (t4 + 4 < SEQ) ? bf2f(row[t4 + 4]) : 0.f;
;   o[0] = w0 * xm + w1 * x0 + w2 * x1 + bias;
;   o[1] = w0 * x0 + w1 * x1 + w2 * x2 + bias;
;   o[2] = w0 * x1 + w1 * x2 + w2 * x3 + bias;
;   o[3] = w0 * x2 + w1 * x3 + w2 * xp + bias;
; }
; DI void hyena_item(const P& p, int l, int c, char* smem) {
;     ...
;       for (int rq = 0; rq < 4; ++rq) {
;         const int bq = 32 * I + 8 * rq + 4 * g;
;         const int t4 = 128 * a + bq;
;         float px[4];
;         sconv4(rowx, t4, x0, x1, x2, xb, px);
;         const uint2 zv = *(const uint2*)(U + (bt * 64 + a) * 136 + bq);
;         const uint2 gv = *(const uint2*)(rowg + t4);
;         const float z1[4] = {bflo(zv.x), bfhi(zv.x), bflo(zv.y), bfhi(zv.y)};
;         const float gt[4] = {bflo(gv.x), bfhi(gv.x), bflo(gv.y), bfhi(gv.y)};
;         float yy[4];
; #pragma unroll
;         for (int j = 0; j < 4; ++j) yy[j] = px[j] * (acc[I][4 * rq + j] * invn1 + z1[j] * d1) * siluf(gt[j]);
;         uint2 ov; ov.x = pack2(yy[0], yy[1]); ov.y = pack2(yy[2], yy[3]);
;         *(uint2*)(dst + t4) = ov;
	v_lshlrev_b32_e32 v174, 16, v160
	v_and_b32_e32 v175, 0xffff0000, v160
	v_lshlrev_b32_e32 v176, 16, v161
	v_and_b32_e32 v177, 0xffff0000, v161
	v_mul_f32_e32 v174, v68, v174
	v_mul_f32_e32 v175, v68, v175
	v_mul_f32_e32 v176, v68, v176
	v_mul_f32_e32 v177, v68, v177
	v_fmac_f32_e32 v174, v238, v32
	v_fmac_f32_e32 v175, v238, v33
	v_fmac_f32_e32 v176, v238, v34
	v_fmac_f32_e32 v177, v238, v35
	v_mul_f32_e32 v174, v178, v174
	v_mul_f32_e32 v175, v179, v175
	v_mul_f32_e32 v176, v180, v176
	v_mul_f32_e32 v177, v181, v177
	v_lshlrev_b32_e32 v168, 16, v116
	v_and_b32_e32 v169, 0xffff0000, v116
	v_lshlrev_b32_e32 v170, 16, v117
	v_and_b32_e32 v171, 0xffff0000, v117
	v_mul_f32_e32 v178, 0xbfb8aa3b, v168
	v_mul_f32_e32 v179, 0xbfb8aa3b, v169
	v_mul_f32_e32 v180, 0xbfb8aa3b, v170
	v_mul_f32_e32 v181, 0xbfb8aa3b, v171
	v_exp_f32_e32 v178, v178
	v_exp_f32_e32 v179, v179
	v_exp_f32_e32 v180, v180
	v_exp_f32_e32 v181, v181
	v_add_f32_e32 v178, 1.0, v178
	v_add_f32_e32 v179, 1.0, v179
	v_add_f32_e32 v180, 1.0, v180
	v_add_f32_e32 v181, 1.0, v181
	v_rcp_f32_e32 v178, v178
	v_rcp_f32_e32 v179, v179
	v_rcp_f32_e32 v180, v180
	v_rcp_f32_e32 v181, v181
	v_mul_f32_e32 v178, v178, v168
	v_mul_f32_e32 v179, v179, v169
	v_mul_f32_e32 v180, v180, v170
	v_mul_f32_e32 v181, v181, v171
	v_mul_f32_e32 v174, v174, v178
	v_mul_f32_e32 v175, v175, v179
	v_mul_f32_e32 v176, v176, v180
	v_mul_f32_e32 v177, v177, v181
	v_cvt_pk_bf16_f32 v182, v174, v175
	v_cvt_pk_bf16_f32 v183, v176, v177
	global_store_dwordx2 v234, v[182:183], s[6:7] offset:64
	v_and_b32_e32 v168, 0xffff0000, v118
	v_lshlrev_b32_e32 v169, 16, v119
	v_and_b32_e32 v170, 0xffff0000, v119
	v_lshlrev_b32_e32 v171, 16, v120
	v_and_b32_e32 v172, 0xffff0000, v120
	v_lshlrev_b32_e32 v173, 16, v121
	v_mul_f32_e32 v178, v83, v168
	v_fmac_f32_e32 v178, v82, v169
	v_fmac_f32_e32 v178, v80, v170
	v_add_f32_e32 v178, v70, v178
	v_mul_f32_e32 v179, v83, v169
	v_fmac_f32_e32 v179, v82, v170
	v_fmac_f32_e32 v179, v80, v171
	v_add_f32_e32 v179, v70, v179
	v_mul_f32_e32 v180, v83, v170
	v_fmac_f32_e32 v180, v82, v171
	v_fmac_f32_e32 v180, v80, v172
	v_add_f32_e32 v180, v70, v180
	v_mul_f32_e32 v181, v83, v171
	v_fmac_f32_e32 v181, v82, v172
	v_fmac_f32_e32 v181, v80, v173
	v_add_f32_e32 v181, v70, v181
	v_lshlrev_b32_e32 v174, 16, v162
	v_and_b32_e32 v175, 0xffff0000, v162
	v_lshlrev_b32_e32 v176, 16, v163
	v_and_b32_e32 v177, 0xffff0000, v163
	v_mul_f32_e32 v174, v68, v174
	v_mul_f32_e32 v175, v68, v175
	v_mul_f32_e32 v176, v68, v176
	v_mul_f32_e32 v177, v68, v177
	v_fmac_f32_e32 v174, v238, v36
	v_fmac_f32_e32 v175, v238, v37
	v_fmac_f32_e32 v176, v238, v38
	v_fmac_f32_e32 v177, v238, v39
	v_mul_f32_e32 v174, v178, v174
	v_mul_f32_e32 v175, v179, v175
	v_mul_f32_e32 v176, v180, v176
	v_mul_f32_e32 v177, v181, v177
	v_lshlrev_b32_e32 v168, 16, v122
	v_and_b32_e32 v169, 0xffff0000, v122
	v_lshlrev_b32_e32 v170, 16, v123
	v_and_b32_e32 v171, 0xffff0000, v123
	v_mul_f32_e32 v178, 0xbfb8aa3b, v168
	v_mul_f32_e32 v179, 0xbfb8aa3b, v169
	v_mul_f32_e32 v180, 0xbfb8aa3b, v170
	v_mul_f32_e32 v181, 0xbfb8aa3b, v171
	v_exp_f32_e32 v178, v178
	v_exp_f32_e32 v179, v179
	v_exp_f32_e32 v180, v180
	v_exp_f32_e32 v181, v181
	v_add_f32_e32 v178, 1.0, v178
	v_add_f32_e32 v179, 1.0, v179
	v_add_f32_e32 v180, 1.0, v180
	v_add_f32_e32 v181, 1.0, v181
	v_rcp_f32_e32 v178, v178
	v_rcp_f32_e32 v179, v179
	v_rcp_f32_e32 v180, v180
	v_rcp_f32_e32 v181, v181
	v_mul_f32_e32 v178, v178, v168
	v_mul_f32_e32 v179, v179, v169
	v_mul_f32_e32 v180, v180, v170
	v_mul_f32_e32 v181, v181, v171
	v_mul_f32_e32 v174, v174, v178
	v_mul_f32_e32 v175, v175, v179
	v_mul_f32_e32 v176, v176, v180
	v_mul_f32_e32 v177, v177, v181
	v_cvt_pk_bf16_f32 v182, v174, v175
	v_cvt_pk_bf16_f32 v183, v176, v177
	global_store_dwordx2 v234, v[182:183], s[6:7] offset:80
	v_and_b32_e32 v168, 0xffff0000, v124
	v_lshlrev_b32_e32 v169, 16, v125
	v_and_b32_e32 v170, 0xffff0000, v125
	v_lshlrev_b32_e32 v171, 16, v126
	v_and_b32_e32 v172, 0xffff0000, v126
	v_lshlrev_b32_e32 v173, 16, v127
	v_mul_f32_e32 v178, v83, v168
	v_fmac_f32_e32 v178, v82, v169
	v_fmac_f32_e32 v178, v80, v170
	v_add_f32_e32 v178, v70, v178
	v_mul_f32_e32 v179, v83, v169
	v_fmac_f32_e32 v179, v82, v170
	v_fmac_f32_e32 v179, v80, v171
	v_add_f32_e32 v179, v70, v179
	v_mul_f32_e32 v180, v83, v170
	v_fmac_f32_e32 v180, v82, v171
	v_fmac_f32_e32 v180, v80, v172
	v_add_f32_e32 v180, v70, v180
	v_mul_f32_e32 v181, v83, v171
	v_fmac_f32_e32 v181, v82, v172
	v_fmac_f32_e32 v181, v80, v173
	v_add_f32_e32 v181, v70, v181
	v_lshlrev_b32_e32 v174, 16, v164
	v_and_b32_e32 v175, 0xffff0000, v164
	v_lshlrev_b32_e32 v176, 16, v165
	v_and_b32_e32 v177, 0xffff0000, v165
	v_mul_f32_e32 v174, v68, v174
	v_mul_f32_e32 v175, v68, v175
	v_mul_f32_e32 v176, v68, v176
	v_mul_f32_e32 v177, v68, v177
	v_fmac_f32_e32 v174, v238, v40
	v_fmac_f32_e32 v175, v238, v41
	v_fmac_f32_e32 v176, v238, v42
	v_fmac_f32_e32 v177, v238, v43
	v_mul_f32_e32 v174, v178, v174
	v_mul_f32_e32 v175, v179, v175
	v_mul_f32_e32 v176, v180, v176
	v_mul_f32_e32 v177, v181, v177
	v_lshlrev_b32_e32 v168, 16, v128
	v_and_b32_e32 v169, 0xffff0000, v128
	v_lshlrev_b32_e32 v170, 16, v129
	v_and_b32_e32 v171, 0xffff0000, v129
	v_mul_f32_e32 v178, 0xbfb8aa3b, v168
	v_mul_f32_e32 v179, 0xbfb8aa3b, v169
	v_mul_f32_e32 v180, 0xbfb8aa3b, v170
	v_mul_f32_e32 v181, 0xbfb8aa3b, v171
	v_exp_f32_e32 v178, v178
	v_exp_f32_e32 v179, v179
	v_exp_f32_e32 v180, v180
	v_exp_f32_e32 v181, v181
	v_add_f32_e32 v178, 1.0, v178
	v_add_f32_e32 v179, 1.0, v179
	v_add_f32_e32 v180, 1.0, v180
	v_add_f32_e32 v181, 1.0, v181
	v_rcp_f32_e32 v178, v178
	v_rcp_f32_e32 v179, v179
	v_rcp_f32_e32 v180, v180
; DI float bf2f(unsigned v) { return __uint_as_float(v << 16); }
; DI float bflo(unsigned v) { return __uint_as_float(v << 16); }
; DI float bfhi(unsigned v) { return __uint_as_float(v & 0xffff0000u); }
; DI float siluf(float x) { return x * __builtin_amdgcn_rcpf(1.f + __expf(-x)); }
; DI void sconv4(const u16* row, int t4, float w0, float w1, float w2, float bias, float (&o)[4]) {
;   const uint2 v = *(const uint2*)(row + t4);
;   const float x0 = bflo(v.x), x1 = bfhi(v.x), x2 = bflo(v.y), x3 = bfhi(v.y);
;   const float xm = (t4 > 0) ? bf2f(row[t4 - 1]) : 0.f;
;   const float xp = (t4 + 4 < SEQ) ? bf2f(row[t4 + 4]) : 0.f;
;   o[0] = w0 * xm + w1 * x0 + w2 * x1 + bias;
;   o[1] = w0 * x0 + w1 * x1 + w2 * x2 + bias;
;   o[2] = w0 * x1 + w1 * x2 + w2 * x3 + bias;
;   o[3] = w0 * x2 + w1 * x3 + w2 * xp + bias;
; }
; DI void hyena_item(const P& p, int l, int c, char* smem) {
;     ...
;       for (int rq = 0; rq < 4; ++rq) {
;         const int bq = 32 * I + 8 * rq + 4 * g;
;         const int t4 = 128 * a + bq;
;         float px[4];
;         sconv4(rowx, t4, x0, x1, x2, xb, px);
;         const uint2 zv = *(const uint2*)(U + (bt * 64 + a) * 136 + bq);
;         const uint2 gv = *(const uint2*)(rowg + t4);
;         const float z1[4] = {bflo(zv.x), bfhi(zv.x), bflo(zv.y), bfhi(zv.y)};
;         const float gt[4] = {bflo(gv.x), bfhi(gv.x), bflo(gv.y), bfhi(gv.y)};
;         float yy[4];
; #pragma unroll
;         for (int j = 0; j < 4; ++j) yy[j] = px[j] * (acc[I][4 * rq + j] * invn1 + z1[j] * d1) * siluf(gt[j]);
;         uint2 ov; ov.x = pack2(yy[0], yy[1]); ov.y = pack2(yy[2], yy[3]);
;         *(uint2*)(dst + t4) = ov;
	v_rcp_f32_e32 v181, v181
	v_mul_f32_e32 v178, v178, v168
	v_mul_f32_e32 v179, v179, v169
	v_mul_f32_e32 v180, v180, v170
	v_mul_f32_e32 v181, v181, v171
	v_mul_f32_e32 v174, v174, v178
	v_mul_f32_e32 v175, v175, v179
	v_mul_f32_e32 v176, v176, v180
	v_mul_f32_e32 v177, v177, v181
	v_cvt_pk_bf16_f32 v182, v174, v175
	v_cvt_pk_bf16_f32 v183, v176, v177
	global_store_dwordx2 v234, v[182:183], s[6:7] offset:96
	v_and_b32_e32 v168, 0xffff0000, v130
	v_lshlrev_b32_e32 v169, 16, v131
	v_and_b32_e32 v170, 0xffff0000, v131
	v_lshlrev_b32_e32 v171, 16, v132
	v_and_b32_e32 v172, 0xffff0000, v132
	v_lshlrev_b32_e32 v173, 16, v133
	v_mul_f32_e32 v178, v83, v168
	v_fmac_f32_e32 v178, v82, v169
	v_fmac_f32_e32 v178, v80, v170
	v_add_f32_e32 v178, v70, v178
	v_mul_f32_e32 v179, v83, v169
	v_fmac_f32_e32 v179, v82, v170
	v_fmac_f32_e32 v179, v80, v171
	v_add_f32_e32 v179, v70, v179
	v_mul_f32_e32 v180, v83, v170
	v_fmac_f32_e32 v180, v82, v171
	v_fmac_f32_e32 v180, v80, v172
	v_add_f32_e32 v180, v70, v180
	v_mul_f32_e32 v181, v83, v171
	v_fmac_f32_e32 v181, v82, v172
	v_fmac_f32_e32 v181, v80, v173
	v_add_f32_e32 v181, v70, v181
	v_lshlrev_b32_e32 v174, 16, v166
	v_and_b32_e32 v175, 0xffff0000, v166
	v_lshlrev_b32_e32 v176, 16, v167
	v_and_b32_e32 v177, 0xffff0000, v167
	v_mul_f32_e32 v174, v68, v174
	v_mul_f32_e32 v175, v68, v175
	v_mul_f32_e32 v176, v68, v176
	v_mul_f32_e32 v177, v68, v177
	v_fmac_f32_e32 v174, v238, v44
	v_fmac_f32_e32 v175, v238, v45
	v_fmac_f32_e32 v176, v238, v46
	v_fmac_f32_e32 v177, v238, v47
	v_mul_f32_e32 v174, v178, v174
	v_mul_f32_e32 v175, v179, v175
	v_mul_f32_e32 v176, v180, v176
	v_mul_f32_e32 v177, v181, v177
	v_lshlrev_b32_e32 v168, 16, v134
	v_and_b32_e32 v169, 0xffff0000, v134
	v_lshlrev_b32_e32 v170, 16, v135
	v_and_b32_e32 v171, 0xffff0000, v135
	v_mul_f32_e32 v178, 0xbfb8aa3b, v168
	v_mul_f32_e32 v179, 0xbfb8aa3b, v169
	v_mul_f32_e32 v180, 0xbfb8aa3b, v170
	v_mul_f32_e32 v181, 0xbfb8aa3b, v171
	v_exp_f32_e32 v178, v178
	v_exp_f32_e32 v179, v179
	v_exp_f32_e32 v180, v180
	v_exp_f32_e32 v181, v181
	v_add_f32_e32 v178, 1.0, v178
	v_add_f32_e32 v179, 1.0, v179
	v_add_f32_e32 v180, 1.0, v180
	v_add_f32_e32 v181, 1.0, v181
	v_rcp_f32_e32 v178, v178
	v_rcp_f32_e32 v179, v179
	v_rcp_f32_e32 v180, v180
	v_rcp_f32_e32 v181, v181
	v_mul_f32_e32 v178, v178, v168
	v_mul_f32_e32 v179, v179, v169
	v_mul_f32_e32 v180, v180, v170
	v_mul_f32_e32 v181, v181, v171
	v_mul_f32_e32 v174, v174, v178
	v_mul_f32_e32 v175, v175, v179
	v_mul_f32_e32 v176, v176, v180
	v_mul_f32_e32 v177, v177, v181
	v_cvt_pk_bf16_f32 v182, v174, v175
	v_cvt_pk_bf16_f32 v183, v176, v177
	global_store_dwordx2 v234, v[182:183], s[6:7] offset:112
	global_load_dwordx4 v[88:91], v234, s[98:99] offset:192
	global_load_dwordx2 v[92:93], v234, s[100:101] offset:192
	global_load_dwordx4 v[94:97], v234, s[98:99] offset:208
	global_load_dwordx2 v[98:99], v234, s[100:101] offset:208
	global_load_dwordx4 v[100:103], v234, s[98:99] offset:224
	global_load_dwordx2 v[104:105], v234, s[100:101] offset:224
	global_load_dwordx4 v[106:109], v234, s[98:99] offset:240
	global_load_dwordx2 v[110:111], v234, s[100:101] offset:240
	s_waitcnt vmcnt(12)
	ds_read_b64 v[160:161], v235 offset:128
	ds_read_b64 v[162:163], v235 offset:144
	ds_read_b64 v[164:165], v235 offset:160
	ds_read_b64 v[166:167], v235 offset:176
	v_and_b32_e32 v168, 0xffff0000, v136
	v_lshlrev_b32_e32 v169, 16, v137
	v_and_b32_e32 v170, 0xffff0000, v137
	v_lshlrev_b32_e32 v171, 16, v138
	v_and_b32_e32 v172, 0xffff0000, v138
	v_lshlrev_b32_e32 v173, 16, v139
	v_mul_f32_e32 v178, v83, v168
	v_fmac_f32_e32 v178, v82, v169
	v_fmac_f32_e32 v178, v80, v170
	v_add_f32_e32 v178, v70, v178
	v_mul_f32_e32 v179, v83, v169
	v_fmac_f32_e32 v179, v82, v170
	v_fmac_f32_e32 v179, v80, v171
	v_add_f32_e32 v179, v70, v179
	v_mul_f32_e32 v180, v83, v170
	v_fmac_f32_e32 v180, v82, v171
	v_fmac_f32_e32 v180, v80, v172
	v_add_f32_e32 v180, v70, v180
	v_mul_f32_e32 v181, v83, v171
	v_fmac_f32_e32 v181, v82, v172
	v_fmac_f32_e32 v181, v80, v173
	v_add_f32_e32 v181, v70, v181
	s_waitcnt lgkmcnt(0)
	v_lshlrev_b32_e32 v174, 16, v160
	v_and_b32_e32 v175, 0xffff0000, v160
	v_lshlrev_b32_e32 v176, 16, v161
	v_and_b32_e32 v177, 0xffff0000, v161
	v_mul_f32_e32 v174, v68, v174
	v_mul_f32_e32 v175, v68, v175
	v_mul_f32_e32 v176, v68, v176
	v_mul_f32_e32 v177, v68, v177
	v_fmac_f32_e32 v174, v238, v16
	v_fmac_f32_e32 v175, v238, v17
	v_fmac_f32_e32 v176, v238, v18
	v_fmac_f32_e32 v177, v238, v19
	v_mul_f32_e32 v174, v178, v174
	v_mul_f32_e32 v175, v179, v175
	v_mul_f32_e32 v176, v180, v176
	v_mul_f32_e32 v177, v181, v177
	v_lshlrev_b32_e32 v168, 16, v140
	v_and_b32_e32 v169, 0xffff0000, v140
	v_lshlrev_b32_e32 v170, 16, v141
	v_and_b32_e32 v171, 0xffff0000, v141
	v_mul_f32_e32 v178, 0xbfb8aa3b, v168
	v_mul_f32_e32 v179, 0xbfb8aa3b, v169
	v_mul_f32_e32 v180, 0xbfb8aa3b, v170
	v_mul_f32_e32 v181, 0xbfb8aa3b, v171
	v_exp_f32_e32 v178, v178
	v_exp_f32_e32 v179, v179
	v_exp_f32_e32 v180, v180
	v_exp_f32_e32 v181, v181
	v_add_f32_e32 v178, 1.0, v178
	v_add_f32_e32 v179, 1.0, v179
	v_add_f32_e32 v180, 1.0, v180
	v_add_f32_e32 v181, 1.0, v181
	v_rcp_f32_e32 v178, v178
	v_rcp_f32_e32 v179, v179
	v_rcp_f32_e32 v180, v180
	v_rcp_f32_e32 v181, v181
	v_mul_f32_e32 v178, v178, v168
	v_mul_f32_e32 v179, v179, v169
	v_mul_f32_e32 v180, v180, v170
	v_mul_f32_e32 v181, v181, v171
	v_mul_f32_e32 v174, v174, v178
	v_mul_f32_e32 v175, v175, v179
	v_mul_f32_e32 v176, v176, v180
	v_mul_f32_e32 v177, v177, v181
	v_cvt_pk_bf16_f32 v182, v174, v175
	v_cvt_pk_bf16_f32 v183, v176, v177
	global_store_dwordx2 v234, v[182:183], s[6:7] offset:128
	v_and_b32_e32 v168, 0xffff0000, v142
; DI float bf2f(unsigned v) { return __uint_as_float(v << 16); }
; DI float bflo(unsigned v) { return __uint_as_float(v << 16); }
; DI float bfhi(unsigned v) { return __uint_as_float(v & 0xffff0000u); }
; DI float siluf(float x) { return x * __builtin_amdgcn_rcpf(1.f + __expf(-x)); }
; DI void sconv4(const u16* row, int t4, float w0, float w1, float w2, float bias, float (&o)[4]) {
;   const uint2 v = *(const uint2*)(row + t4);
;   const float x0 = bflo(v.x), x1 = bfhi(v.x), x2 = bflo(v.y), x3 = bfhi(v.y);
;   const float xm = (t4 > 0) ? bf2f(row[t4 - 1]) : 0.f;
;   const float xp = (t4 + 4 < SEQ) ? bf2f(row[t4 + 4]) : 0.f;
;   o[0] = w0 * xm + w1 * x0 + w2 * x1 + bias;
;   o[1] = w0 * x0 + w1 * x1 + w2 * x2 + bias;
;   o[2] = w0 * x1 + w1 * x2 + w2 * x3 + bias;
;   o[3] = w0 * x2 + w1 * x3 + w2 * xp + bias;
; }
; DI void hyena_item(const P& p, int l, int c, char* smem) {
;     ...
;       for (int rq = 0; rq < 4; ++rq) {
;         const int bq = 32 * I + 8 * rq + 4 * g;
;         const int t4 = 128 * a + bq;
;         float px[4];
;         sconv4(rowx, t4, x0, x1, x2, xb, px);
;         const uint2 zv = *(const uint2*)(U + (bt * 64 + a) * 136 + bq);
;         const uint2 gv = *(const uint2*)(rowg + t4);
;         const float z1[4] = {bflo(zv.x), bfhi(zv.x), bflo(zv.y), bfhi(zv.y)};
;         const float gt[4] = {bflo(gv.x), bfhi(gv.x), bflo(gv.y), bfhi(gv.y)};
;         float yy[4];
; #pragma unroll
;         for (int j = 0; j < 4; ++j) yy[j] = px[j] * (acc[I][4 * rq + j] * invn1 + z1[j] * d1) * siluf(gt[j]);
;         uint2 ov; ov.x = pack2(yy[0], yy[1]); ov.y = pack2(yy[2], yy[3]);
;         *(uint2*)(dst + t4) = ov;
	v_lshlrev_b32_e32 v169, 16, v143
	v_and_b32_e32 v170, 0xffff0000, v143
	v_lshlrev_b32_e32 v171, 16, v144
	v_and_b32_e32 v172, 0xffff0000, v144
	v_lshlrev_b32_e32 v173, 16, v145
	v_mul_f32_e32 v178, v83, v168
	v_fmac_f32_e32 v178, v82, v169
	v_fmac_f32_e32 v178, v80, v170
	v_add_f32_e32 v178, v70, v178
	v_mul_f32_e32 v179, v83, v169
	v_fmac_f32_e32 v179, v82, v170
	v_fmac_f32_e32 v179, v80, v171
	v_add_f32_e32 v179, v70, v179
	v_mul_f32_e32 v180, v83, v170
	v_fmac_f32_e32 v180, v82, v171
	v_fmac_f32_e32 v180, v80, v172
	v_add_f32_e32 v180, v70, v180
	v_mul_f32_e32 v181, v83, v171
	v_fmac_f32_e32 v181, v82, v172
	v_fmac_f32_e32 v181, v80, v173
	v_add_f32_e32 v181, v70, v181
	v_lshlrev_b32_e32 v174, 16, v162
	v_and_b32_e32 v175, 0xffff0000, v162
	v_lshlrev_b32_e32 v176, 16, v163
	v_and_b32_e32 v177, 0xffff0000, v163
	v_mul_f32_e32 v174, v68, v174
	v_mul_f32_e32 v175, v68, v175
	v_mul_f32_e32 v176, v68, v176
	v_mul_f32_e32 v177, v68, v177
	v_fmac_f32_e32 v174, v238, v20
	v_fmac_f32_e32 v175, v238, v21
	v_fmac_f32_e32 v176, v238, v22
	v_fmac_f32_e32 v177, v238, v23
	v_mul_f32_e32 v174, v178, v174
	v_mul_f32_e32 v175, v179, v175
	v_mul_f32_e32 v176, v180, v176
	v_mul_f32_e32 v177, v181, v177
	v_lshlrev_b32_e32 v168, 16, v146
	v_and_b32_e32 v169, 0xffff0000, v146
	v_lshlrev_b32_e32 v170, 16, v147
	v_and_b32_e32 v171, 0xffff0000, v147
	v_mul_f32_e32 v178, 0xbfb8aa3b, v168
	v_mul_f32_e32 v179, 0xbfb8aa3b, v169
	v_mul_f32_e32 v180, 0xbfb8aa3b, v170
	v_mul_f32_e32 v181, 0xbfb8aa3b, v171
	v_exp_f32_e32 v178, v178
	v_exp_f32_e32 v179, v179
	v_exp_f32_e32 v180, v180
	v_exp_f32_e32 v181, v181
	v_add_f32_e32 v178, 1.0, v178
	v_add_f32_e32 v179, 1.0, v179
	v_add_f32_e32 v180, 1.0, v180
	v_add_f32_e32 v181, 1.0, v181
	v_rcp_f32_e32 v178, v178
	v_rcp_f32_e32 v179, v179
	v_rcp_f32_e32 v180, v180
	v_rcp_f32_e32 v181, v181
	v_mul_f32_e32 v178, v178, v168
	v_mul_f32_e32 v179, v179, v169
	v_mul_f32_e32 v180, v180, v170
	v_mul_f32_e32 v181, v181, v171
	v_mul_f32_e32 v174, v174, v178
	v_mul_f32_e32 v175, v175, v179
	v_mul_f32_e32 v176, v176, v180
	v_mul_f32_e32 v177, v177, v181
	v_cvt_pk_bf16_f32 v182, v174, v175
	v_cvt_pk_bf16_f32 v183, v176, v177
	global_store_dwordx2 v234, v[182:183], s[6:7] offset:144
	v_and_b32_e32 v168, 0xffff0000, v148
	v_lshlrev_b32_e32 v169, 16, v149
	v_and_b32_e32 v170, 0xffff0000, v149
	v_lshlrev_b32_e32 v171, 16, v150
	v_and_b32_e32 v172, 0xffff0000, v150
	v_lshlrev_b32_e32 v173, 16, v151
	v_mul_f32_e32 v178, v83, v168
	v_fmac_f32_e32 v178, v82, v169
	v_fmac_f32_e32 v178, v80, v170
	v_add_f32_e32 v178, v70, v178
	v_mul_f32_e32 v179, v83, v169
	v_fmac_f32_e32 v179, v82, v170
	v_fmac_f32_e32 v179, v80, v171
	v_add_f32_e32 v179, v70, v179
	v_mul_f32_e32 v180, v83, v170
	v_fmac_f32_e32 v180, v82, v171
	v_fmac_f32_e32 v180, v80, v172
	v_add_f32_e32 v180, v70, v180
	v_mul_f32_e32 v181, v83, v171
	v_fmac_f32_e32 v181, v82, v172
	v_fmac_f32_e32 v181, v80, v173
	v_add_f32_e32 v181, v70, v181
	v_lshlrev_b32_e32 v174, 16, v164
	v_and_b32_e32 v175, 0xffff0000, v164
	v_lshlrev_b32_e32 v176, 16, v165
	v_and_b32_e32 v177, 0xffff0000, v165
	v_mul_f32_e32 v174, v68, v174
	v_mul_f32_e32 v175, v68, v175
	v_mul_f32_e32 v176, v68, v176
	v_mul_f32_e32 v177, v68, v177
	v_fmac_f32_e32 v174, v238, v24
	v_fmac_f32_e32 v175, v238, v25
	v_fmac_f32_e32 v176, v238, v26
	v_fmac_f32_e32 v177, v238, v27
	v_mul_f32_e32 v174, v178, v174
	v_mul_f32_e32 v175, v179, v175
	v_mul_f32_e32 v176, v180, v176
	v_mul_f32_e32 v177, v181, v177
	v_lshlrev_b32_e32 v168, 16, v152
	v_and_b32_e32 v169, 0xffff0000, v152
	v_lshlrev_b32_e32 v170, 16, v153
	v_and_b32_e32 v171, 0xffff0000, v153
	v_mul_f32_e32 v178, 0xbfb8aa3b, v168
	v_mul_f32_e32 v179, 0xbfb8aa3b, v169
	v_mul_f32_e32 v180, 0xbfb8aa3b, v170
	v_mul_f32_e32 v181, 0xbfb8aa3b, v171
	v_exp_f32_e32 v178, v178
	v_exp_f32_e32 v179, v179
	v_exp_f32_e32 v180, v180
	v_exp_f32_e32 v181, v181
	v_add_f32_e32 v178, 1.0, v178
	v_add_f32_e32 v179, 1.0, v179
	v_add_f32_e32 v180, 1.0, v180
	v_add_f32_e32 v181, 1.0, v181
	v_rcp_f32_e32 v178, v178
	v_rcp_f32_e32 v179, v179
	v_rcp_f32_e32 v180, v180
	v_rcp_f32_e32 v181, v181
	v_mul_f32_e32 v178, v178, v168
	v_mul_f32_e32 v179, v179, v169
	v_mul_f32_e32 v180, v180, v170
	v_mul_f32_e32 v181, v181, v171
	v_mul_f32_e32 v174, v174, v178
	v_mul_f32_e32 v175, v175, v179
	v_mul_f32_e32 v176, v176, v180
	v_mul_f32_e32 v177, v177, v181
	v_cvt_pk_bf16_f32 v182, v174, v175
	v_cvt_pk_bf16_f32 v183, v176, v177
	global_store_dwordx2 v234, v[182:183], s[6:7] offset:160
	v_and_b32_e32 v168, 0xffff0000, v154
	v_lshlrev_b32_e32 v169, 16, v155
	v_and_b32_e32 v170, 0xffff0000, v155
	v_lshlrev_b32_e32 v171, 16, v156
	v_and_b32_e32 v172, 0xffff0000, v156
	v_lshlrev_b32_e32 v173, 16, v157
	v_mul_f32_e32 v178, v83, v168
	v_fmac_f32_e32 v178, v82, v169
	v_fmac_f32_e32 v178, v80, v170
	v_add_f32_e32 v178, v70, v178
	v_mul_f32_e32 v179, v83, v169
	v_fmac_f32_e32 v179, v82, v170
	v_fmac_f32_e32 v179, v80, v171
	v_add_f32_e32 v179, v70, v179
	v_mul_f32_e32 v180, v83, v170
	v_fmac_f32_e32 v180, v82, v171
	v_fmac_f32_e32 v180, v80, v172
	v_add_f32_e32 v180, v70, v180
	v_mul_f32_e32 v181, v83, v171
	v_fmac_f32_e32 v181, v82, v172
	v_fmac_f32_e32 v181, v80, v173
	v_add_f32_e32 v181, v70, v181
	v_lshlrev_b32_e32 v174, 16, v166
	v_and_b32_e32 v175, 0xffff0000, v166
	v_lshlrev_b32_e32 v176, 16, v167
	v_and_b32_e32 v177, 0xffff0000, v167
	v_mul_f32_e32 v174, v68, v174
	v_mul_f32_e32 v175, v68, v175
	v_mul_f32_e32 v176, v68, v176
	v_mul_f32_e32 v177, v68, v177
	v_fmac_f32_e32 v174, v238, v28
	v_fmac_f32_e32 v175, v238, v29
	v_fmac_f32_e32 v176, v238, v30
	v_fmac_f32_e32 v177, v238, v31
	v_mul_f32_e32 v174, v178, v174
	v_mul_f32_e32 v175, v179, v175
	v_mul_f32_e32 v176, v180, v176
	v_mul_f32_e32 v177, v181, v177
	v_lshlrev_b32_e32 v168, 16, v158
	v_and_b32_e32 v169, 0xffff0000, v158
	v_lshlrev_b32_e32 v170, 16, v159
	v_and_b32_e32 v171, 0xffff0000, v159
	v_mul_f32_e32 v178, 0xbfb8aa3b, v168
	v_mul_f32_e32 v179, 0xbfb8aa3b, v169
	v_mul_f32_e32 v180, 0xbfb8aa3b, v170
	v_mul_f32_e32 v181, 0xbfb8aa3b, v171
	v_exp_f32_e32 v178, v178
	v_exp_f32_e32 v179, v179
	v_exp_f32_e32 v180, v180
	v_exp_f32_e32 v181, v181
	v_add_f32_e32 v178, 1.0, v178
	v_add_f32_e32 v179, 1.0, v179
	v_add_f32_e32 v180, 1.0, v180
	v_add_f32_e32 v181, 1.0, v181
	v_rcp_f32_e32 v178, v178
	v_rcp_f32_e32 v179, v179
	v_rcp_f32_e32 v180, v180
	v_rcp_f32_e32 v181, v181
	v_mul_f32_e32 v178, v178, v168
	v_mul_f32_e32 v179, v179, v169
	v_mul_f32_e32 v180, v180, v170
	v_mul_f32_e32 v181, v181, v171
	v_mul_f32_e32 v174, v174, v178
	v_mul_f32_e32 v175, v175, v179
	v_mul_f32_e32 v176, v176, v180
	v_mul_f32_e32 v177, v177, v181
	v_cvt_pk_bf16_f32 v182, v174, v175
	v_cvt_pk_bf16_f32 v183, v176, v177
	global_store_dwordx2 v234, v[182:183], s[6:7] offset:176
	s_waitcnt vmcnt(4)
; DI float bf2f(unsigned v) { return __uint_as_float(v << 16); }
; DI float bflo(unsigned v) { return __uint_as_float(v << 16); }
; DI float bfhi(unsigned v) { return __uint_as_float(v & 0xffff0000u); }
; DI float siluf(float x) { return x * __builtin_amdgcn_rcpf(1.f + __expf(-x)); }
; DI void sconv4(const u16* row, int t4, float w0, float w1, float w2, float bias, float (&o)[4]) {
;   const uint2 v = *(const uint2*)(row + t4);
;   const float x0 = bflo(v.x), x1 = bfhi(v.x), x2 = bflo(v.y), x3 = bfhi(v.y);
;   const float xm = (t4 > 0) ? bf2f(row[t4 - 1]) : 0.f;
;   const float xp = (t4 + 4 < SEQ) ? bf2f(row[t4 + 4]) : 0.f;
;   o[0] = w0 * xm + w1 * x0 + w2 * x1 + bias;
;   o[1] = w0 * x0 + w1 * x1 + w2 * x2 + bias;
;   o[2] = w0 * x1 + w1 * x2 + w2 * x3 + bias;
;   o[3] = w0 * x2 + w1 * x3 + w2 * xp + bias;
; }
; DI void hyena_item(const P& p, int l, int c, char* smem) {
;     ...
;       for (int rq = 0; rq < 4; ++rq) {
;         const int bq = 32 * I + 8 * rq + 4 * g;
;         const int t4 = 128 * a + bq;
;         float px[4];
;         sconv4(rowx, t4, x0, x1, x2, xb, px);
;         const uint2 zv = *(const uint2*)(U + (bt * 64 + a) * 136 + bq);
;         const uint2 gv = *(const uint2*)(rowg + t4);
;         const float z1[4] = {bflo(zv.x), bfhi(zv.x), bflo(zv.y), bfhi(zv.y)};
;         const float gt[4] = {bflo(gv.x), bfhi(gv.x), bflo(gv.y), bfhi(gv.y)};
;         float yy[4];
; #pragma unroll
;         for (int j = 0; j < 4; ++j) yy[j] = px[j] * (acc[I][4 * rq + j] * invn1 + z1[j] * d1) * siluf(gt[j]);
;         uint2 ov; ov.x = pack2(yy[0], yy[1]); ov.y = pack2(yy[2], yy[3]);
;         *(uint2*)(dst + t4) = ov;
	ds_read_b64 v[160:161], v235 offset:192
	ds_read_b64 v[162:163], v235 offset:208
	ds_read_b64 v[164:165], v235 offset:224
	ds_read_b64 v[166:167], v235 offset:240
	v_and_b32_e32 v168, 0xffff0000, v88
	v_lshlrev_b32_e32 v169, 16, v89
	v_and_b32_e32 v170, 0xffff0000, v89
	v_lshlrev_b32_e32 v171, 16, v90
	v_and_b32_e32 v172, 0xffff0000, v90
	v_lshlrev_b32_e32 v173, 16, v91
	v_mul_f32_e32 v178, v83, v168
	v_fmac_f32_e32 v178, v82, v169
	v_fmac_f32_e32 v178, v80, v170
	v_add_f32_e32 v178, v70, v178
	v_mul_f32_e32 v179, v83, v169
	v_fmac_f32_e32 v179, v82, v170
	v_fmac_f32_e32 v179, v80, v171
	v_add_f32_e32 v179, v70, v179
	v_mul_f32_e32 v180, v83, v170
	v_fmac_f32_e32 v180, v82, v171
	v_fmac_f32_e32 v180, v80, v172
	v_add_f32_e32 v180, v70, v180
	v_mul_f32_e32 v181, v83, v171
	v_fmac_f32_e32 v181, v82, v172
	v_fmac_f32_e32 v181, v80, v173
	v_add_f32_e32 v181, v70, v181
	s_waitcnt lgkmcnt(0)
	v_lshlrev_b32_e32 v174, 16, v160
	v_and_b32_e32 v175, 0xffff0000, v160
	v_lshlrev_b32_e32 v176, 16, v161
	v_and_b32_e32 v177, 0xffff0000, v161
	v_mul_f32_e32 v174, v68, v174
	v_mul_f32_e32 v175, v68, v175
	v_mul_f32_e32 v176, v68, v176
	v_mul_f32_e32 v177, v68, v177
	v_fmac_f32_e32 v174, v238, v0
	v_fmac_f32_e32 v175, v238, v1
	v_fmac_f32_e32 v176, v238, v2
	v_fmac_f32_e32 v177, v238, v3
	v_mul_f32_e32 v174, v178, v174
	v_mul_f32_e32 v175, v179, v175
	v_mul_f32_e32 v176, v180, v176
	v_mul_f32_e32 v177, v181, v177
	v_lshlrev_b32_e32 v168, 16, v92
	v_and_b32_e32 v169, 0xffff0000, v92
	v_lshlrev_b32_e32 v170, 16, v93
	v_and_b32_e32 v171, 0xffff0000, v93
	v_mul_f32_e32 v178, 0xbfb8aa3b, v168
	v_mul_f32_e32 v179, 0xbfb8aa3b, v169
	v_mul_f32_e32 v180, 0xbfb8aa3b, v170
	v_mul_f32_e32 v181, 0xbfb8aa3b, v171
	v_exp_f32_e32 v178, v178
	v_exp_f32_e32 v179, v179
	v_exp_f32_e32 v180, v180
	v_exp_f32_e32 v181, v181
	v_add_f32_e32 v178, 1.0, v178
	v_add_f32_e32 v179, 1.0, v179
	v_add_f32_e32 v180, 1.0, v180
	v_add_f32_e32 v181, 1.0, v181
	v_rcp_f32_e32 v178, v178
	v_rcp_f32_e32 v179, v179
	v_rcp_f32_e32 v180, v180
	v_rcp_f32_e32 v181, v181
	v_mul_f32_e32 v178, v178, v168
	v_mul_f32_e32 v179, v179, v169
	v_mul_f32_e32 v180, v180, v170
	v_mul_f32_e32 v181, v181, v171
	v_mul_f32_e32 v174, v174, v178
	v_mul_f32_e32 v175, v175, v179
	v_mul_f32_e32 v176, v176, v180
	v_mul_f32_e32 v177, v177, v181
	v_cvt_pk_bf16_f32 v182, v174, v175
	v_cvt_pk_bf16_f32 v183, v176, v177
	global_store_dwordx2 v234, v[182:183], s[6:7] offset:192
	v_and_b32_e32 v168, 0xffff0000, v94
	v_lshlrev_b32_e32 v169, 16, v95
	v_and_b32_e32 v170, 0xffff0000, v95
	v_lshlrev_b32_e32 v171, 16, v96
	v_and_b32_e32 v172, 0xffff0000, v96
	v_lshlrev_b32_e32 v173, 16, v97
	v_mul_f32_e32 v178, v83, v168
	v_fmac_f32_e32 v178, v82, v169
	v_fmac_f32_e32 v178, v80, v170
	v_add_f32_e32 v178, v70, v178
	v_mul_f32_e32 v179, v83, v169
	v_fmac_f32_e32 v179, v82, v170
	v_fmac_f32_e32 v179, v80, v171
	v_add_f32_e32 v179, v70, v179
	v_mul_f32_e32 v180, v83, v170
	v_fmac_f32_e32 v180, v82, v171
	v_fmac_f32_e32 v180, v80, v172
	v_add_f32_e32 v180, v70, v180
	v_mul_f32_e32 v181, v83, v171
	v_fmac_f32_e32 v181, v82, v172
	v_fmac_f32_e32 v181, v80, v173
	v_add_f32_e32 v181, v70, v181
	v_lshlrev_b32_e32 v174, 16, v162
	v_and_b32_e32 v175, 0xffff0000, v162
	v_lshlrev_b32_e32 v176, 16, v163
	v_and_b32_e32 v177, 0xffff0000, v163
	v_mul_f32_e32 v174, v68, v174
	v_mul_f32_e32 v175, v68, v175
	v_mul_f32_e32 v176, v68, v176
	v_mul_f32_e32 v177, v68, v177
	v_fmac_f32_e32 v174, v238, v4
	v_fmac_f32_e32 v175, v238, v5
	v_fmac_f32_e32 v176, v238, v6
	v_fmac_f32_e32 v177, v238, v7
	v_mul_f32_e32 v174, v178, v174
	v_mul_f32_e32 v175, v179, v175
	v_mul_f32_e32 v176, v180, v176
	v_mul_f32_e32 v177, v181, v177
	v_lshlrev_b32_e32 v168, 16, v98
	v_and_b32_e32 v169, 0xffff0000, v98
	v_lshlrev_b32_e32 v170, 16, v99
	v_and_b32_e32 v171, 0xffff0000, v99
	v_mul_f32_e32 v178, 0xbfb8aa3b, v168
	v_mul_f32_e32 v179, 0xbfb8aa3b, v169
	v_mul_f32_e32 v180, 0xbfb8aa3b, v170
	v_mul_f32_e32 v181, 0xbfb8aa3b, v171
	v_exp_f32_e32 v178, v178
	v_exp_f32_e32 v179, v179
	v_exp_f32_e32 v180, v180
	v_exp_f32_e32 v181, v181
	v_add_f32_e32 v178, 1.0, v178
	v_add_f32_e32 v179, 1.0, v179
	v_add_f32_e32 v180, 1.0, v180
	v_add_f32_e32 v181, 1.0, v181
	v_rcp_f32_e32 v178, v178
	v_rcp_f32_e32 v179, v179
	v_rcp_f32_e32 v180, v180
	v_rcp_f32_e32 v181, v181
	v_mul_f32_e32 v178, v178, v168
	v_mul_f32_e32 v179, v179, v169
	v_mul_f32_e32 v180, v180, v170
	v_mul_f32_e32 v181, v181, v171
	v_mul_f32_e32 v174, v174, v178
	v_mul_f32_e32 v175, v175, v179
	v_mul_f32_e32 v176, v176, v180
	v_mul_f32_e32 v177, v177, v181
	v_cvt_pk_bf16_f32 v182, v174, v175
	v_cvt_pk_bf16_f32 v183, v176, v177
; DI float bf2f(unsigned v) { return __uint_as_float(v << 16); }
; DI float bflo(unsigned v) { return __uint_as_float(v << 16); }
; DI float bfhi(unsigned v) { return __uint_as_float(v & 0xffff0000u); }
; DI float siluf(float x) { return x * __builtin_amdgcn_rcpf(1.f + __expf(-x)); }
; DI void sconv4(const u16* row, int t4, float w0, float w1, float w2, float bias, float (&o)[4]) {
;   const uint2 v = *(const uint2*)(row + t4);
;   const float x0 = bflo(v.x), x1 = bfhi(v.x), x2 = bflo(v.y), x3 = bfhi(v.y);
;   const float xm = (t4 > 0) ? bf2f(row[t4 - 1]) : 0.f;
;   const float xp = (t4 + 4 < SEQ) ? bf2f(row[t4 + 4]) : 0.f;
;   o[0] = w0 * xm + w1 * x0 + w2 * x1 + bias;
;   o[1] = w0 * x0 + w1 * x1 + w2 * x2 + bias;
;   o[2] = w0 * x1 + w1 * x2 + w2 * x3 + bias;
;   o[3] = w0 * x2 + w1 * x3 + w2 * xp + bias;
; }
; DI void hyena_item(const P& p, int l, int c, char* smem) {
;     ...
;       for (int rq = 0; rq < 4; ++rq) {
;         const int bq = 32 * I + 8 * rq + 4 * g;
;         const int t4 = 128 * a + bq;
;         float px[4];
;         sconv4(rowx, t4, x0, x1, x2, xb, px);
;         const uint2 zv = *(const uint2*)(U + (bt * 64 + a) * 136 + bq);
;         const uint2 gv = *(const uint2*)(rowg + t4);
;         const float z1[4] = {bflo(zv.x), bfhi(zv.x), bflo(zv.y), bfhi(zv.y)};
;         const float gt[4] = {bflo(gv.x), bfhi(gv.x), bflo(gv.y), bfhi(gv.y)};
;         float yy[4];
; #pragma unroll
;         for (int j = 0; j < 4; ++j) yy[j] = px[j] * (acc[I][4 * rq + j] * invn1 + z1[j] * d1) * siluf(gt[j]);
;         uint2 ov; ov.x = pack2(yy[0], yy[1]); ov.y = pack2(yy[2], yy[3]);
;         *(uint2*)(dst + t4) = ov;
	global_store_dwordx2 v234, v[182:183], s[6:7] offset:208
	v_and_b32_e32 v168, 0xffff0000, v100
	v_lshlrev_b32_e32 v169, 16, v101
	v_and_b32_e32 v170, 0xffff0000, v101
	v_lshlrev_b32_e32 v171, 16, v102
	v_and_b32_e32 v172, 0xffff0000, v102
	v_lshlrev_b32_e32 v173, 16, v103
	v_mul_f32_e32 v178, v83, v168
	v_fmac_f32_e32 v178, v82, v169
	v_fmac_f32_e32 v178, v80, v170
	v_add_f32_e32 v178, v70, v178
	v_mul_f32_e32 v179, v83, v169
	v_fmac_f32_e32 v179, v82, v170
	v_fmac_f32_e32 v179, v80, v171
	v_add_f32_e32 v179, v70, v179
	v_mul_f32_e32 v180, v83, v170
	v_fmac_f32_e32 v180, v82, v171
	v_fmac_f32_e32 v180, v80, v172
	v_add_f32_e32 v180, v70, v180
	v_mul_f32_e32 v181, v83, v171
	v_fmac_f32_e32 v181, v82, v172
	v_fmac_f32_e32 v181, v80, v173
	v_add_f32_e32 v181, v70, v181
	v_lshlrev_b32_e32 v174, 16, v164
	v_and_b32_e32 v175, 0xffff0000, v164
	v_lshlrev_b32_e32 v176, 16, v165
	v_and_b32_e32 v177, 0xffff0000, v165
	v_mul_f32_e32 v174, v68, v174
	v_mul_f32_e32 v175, v68, v175
	v_mul_f32_e32 v176, v68, v176
	v_mul_f32_e32 v177, v68, v177
	v_fmac_f32_e32 v174, v238, v8
	v_fmac_f32_e32 v175, v238, v9
	v_fmac_f32_e32 v176, v238, v10
	v_fmac_f32_e32 v177, v238, v11
	v_mul_f32_e32 v174, v178, v174
	v_mul_f32_e32 v175, v179, v175
	v_mul_f32_e32 v176, v180, v176
	v_mul_f32_e32 v177, v181, v177
	v_lshlrev_b32_e32 v168, 16, v104
	v_and_b32_e32 v169, 0xffff0000, v104
	v_lshlrev_b32_e32 v170, 16, v105
	v_and_b32_e32 v171, 0xffff0000, v105
	v_mul_f32_e32 v178, 0xbfb8aa3b, v168
	v_mul_f32_e32 v179, 0xbfb8aa3b, v169
	v_mul_f32_e32 v180, 0xbfb8aa3b, v170
	v_mul_f32_e32 v181, 0xbfb8aa3b, v171
	v_exp_f32_e32 v178, v178
	v_exp_f32_e32 v179, v179
	v_exp_f32_e32 v180, v180
	v_exp_f32_e32 v181, v181
	v_add_f32_e32 v178, 1.0, v178
	v_add_f32_e32 v179, 1.0, v179
	v_add_f32_e32 v180, 1.0, v180
	v_add_f32_e32 v181, 1.0, v181
	v_rcp_f32_e32 v178, v178
	v_rcp_f32_e32 v179, v179
	v_rcp_f32_e32 v180, v180
	v_rcp_f32_e32 v181, v181
	v_mul_f32_e32 v178, v178, v168
	v_mul_f32_e32 v179, v179, v169
	v_mul_f32_e32 v180, v180, v170
	v_mul_f32_e32 v181, v181, v171
	v_mul_f32_e32 v174, v174, v178
	v_mul_f32_e32 v175, v175, v179
	v_mul_f32_e32 v176, v176, v180
	v_mul_f32_e32 v177, v177, v181
	v_cvt_pk_bf16_f32 v182, v174, v175
	v_cvt_pk_bf16_f32 v183, v176, v177
	global_store_dwordx2 v234, v[182:183], s[6:7] offset:224
	v_cmp_ne_u32_e32 vcc, 0x1f84, v233
	s_nop 1
	v_and_b32_e32 v168, 0xffff0000, v106
	v_lshlrev_b32_e32 v169, 16, v107
	v_and_b32_e32 v170, 0xffff0000, v107
	v_lshlrev_b32_e32 v171, 16, v108
	v_and_b32_e32 v172, 0xffff0000, v108
	v_lshlrev_b32_e32 v173, 16, v109
	v_cndmask_b32_e32 v173, 0, v173, vcc
	v_mul_f32_e32 v178, v83, v168
	v_fmac_f32_e32 v178, v82, v169
	v_fmac_f32_e32 v178, v80, v170
	v_add_f32_e32 v178, v70, v178
	v_mul_f32_e32 v179, v83, v169
	v_fmac_f32_e32 v179, v82, v170
	v_fmac_f32_e32 v179, v80, v171
	v_add_f32_e32 v179, v70, v179
	v_mul_f32_e32 v180, v83, v170
	v_fmac_f32_e32 v180, v82, v171
	v_fmac_f32_e32 v180, v80, v172
	v_add_f32_e32 v180, v70, v180
	v_mul_f32_e32 v181, v83, v171
	v_fmac_f32_e32 v181, v82, v172
	v_fmac_f32_e32 v181, v80, v173
	v_add_f32_e32 v181, v70, v181
	v_lshlrev_b32_e32 v174, 16, v166
	v_and_b32_e32 v175, 0xffff0000, v166
	v_lshlrev_b32_e32 v176, 16, v167
	v_and_b32_e32 v177, 0xffff0000, v167
	v_mul_f32_e32 v174, v68, v174
	v_mul_f32_e32 v175, v68, v175
	v_mul_f32_e32 v176, v68, v176
	v_mul_f32_e32 v177, v68, v177
	v_fmac_f32_e32 v174, v238, v12
	v_fmac_f32_e32 v175, v238, v13
	v_fmac_f32_e32 v176, v238, v14
	v_fmac_f32_e32 v177, v238, v15
	v_mul_f32_e32 v174, v178, v174
	v_mul_f32_e32 v175, v179, v175
	v_mul_f32_e32 v176, v180, v176
	v_mul_f32_e32 v177, v181, v177
	v_lshlrev_b32_e32 v168, 16, v110
	v_and_b32_e32 v169, 0xffff0000, v110
	v_lshlrev_b32_e32 v170, 16, v111
	v_and_b32_e32 v171, 0xffff0000, v111
	v_mul_f32_e32 v178, 0xbfb8aa3b, v168
	v_mul_f32_e32 v179, 0xbfb8aa3b, v169
	v_mul_f32_e32 v180, 0xbfb8aa3b, v170
	v_mul_f32_e32 v181, 0xbfb8aa3b, v171
	v_exp_f32_e32 v178, v178
	v_exp_f32_e32 v179, v179
	v_exp_f32_e32 v180, v180
	v_exp_f32_e32 v181, v181
	v_add_f32_e32 v178, 1.0, v178
	v_add_f32_e32 v179, 1.0, v179
	v_add_f32_e32 v180, 1.0, v180
	v_add_f32_e32 v181, 1.0, v181
	v_rcp_f32_e32 v178, v178
	v_rcp_f32_e32 v179, v179
	v_rcp_f32_e32 v180, v180
	v_rcp_f32_e32 v181, v181
	v_mul_f32_e32 v178, v178, v168
	v_mul_f32_e32 v179, v179, v169
	v_mul_f32_e32 v180, v180, v170
	v_mul_f32_e32 v181, v181, v171
	v_mul_f32_e32 v174, v174, v178
	v_mul_f32_e32 v175, v175, v179
	v_mul_f32_e32 v176, v176, v180
	v_mul_f32_e32 v177, v177, v181
	v_cvt_pk_bf16_f32 v182, v174, v175
	v_cvt_pk_bf16_f32 v183, v176, v177
	global_store_dwordx2 v234, v[182:183], s[6:7] offset:240
